# EpiPair<0> (swiglu) epilogue of both FFN gate/up GEMMs hand-rewritten group-wise: no s_nop, scalar mul/add pairs packed, SSQ loads issued before the epilogue-align barrier; plus attention pk split (bi
# speedup vs baseline: 1.0094x; 1.0094x over previous
.LBB0_311:
	s_add_u32 s4, s62, 0xfffc0080
	s_addc_u32 s5, s63, -1
	s_add_i32 s84, 0, 0x10000
	s_cmp_eq_u32 s82, 12
	s_cselect_b32 s65, s33, s5
	s_cselect_b32 s64, s36, s4
	s_cselect_b32 s35, s53, s79
	s_cselect_b32 s34, s55, s75
	s_add_i32 s4, 0, 0x14000
	v_add_u32_e32 v164, s84, v143
	v_add_u32_e32 v180, s4, v143
	ds_read_b128 v[138:141], v164
	ds_read_b128 v[156:159], v164 offset:1024
	ds_read_b128 v[160:163], v164 offset:2048
	ds_read_b128 v[164:167], v164 offset:3072
	ds_read_b128 v[168:171], v180
	ds_read_b128 v[172:175], v180 offset:1024
	ds_read_b128 v[176:179], v180 offset:2048
	ds_read_b128 v[204:207], v180 offset:3072
	v_lshl_add_u64 v[180:181], s[62:63], 0, v[134:135]
	s_add_i32 m0, s68, 0xc000
	ds_read_b128 v[208:211], v155
	ds_read_b128 v[212:215], v155 offset:1024
	ds_read_b128 v[216:219], v155 offset:2048
	ds_read_b128 v[220:223], v155 offset:3072
	ds_read_b128 v[224:227], v155 offset:4096
	ds_read_b128 v[228:231], v155 offset:5120
	ds_read_b128 v[232:235], v155 offset:6144
	ds_read_b128 v[236:239], v155 offset:7168
	global_load_lds_dwordx4 v[180:181], off
	v_lshl_add_u64 v[180:181], s[62:63], 0, v[136:137]
	s_add_i32 m0, s68, 0xe000
	s_nop 0
	global_load_lds_dwordx4 v[180:181], off
	s_waitcnt vmcnt(8)
	s_waitcnt lgkmcnt(0)
	s_barrier
	s_setprio 1
	s_waitcnt lgkmcnt(0)
	v_mfma_f32_16x16x32_bf16 v[124:127], v[138:141], v[208:211], v[124:127]
	v_mfma_f32_16x16x32_bf16 v[120:123], v[160:163], v[208:211], v[120:123]
	v_mfma_f32_16x16x32_bf16 v[108:111], v[138:141], v[216:219], v[108:111]
	v_mfma_f32_16x16x32_bf16 v[104:107], v[160:163], v[216:219], v[104:107]
	v_mfma_f32_16x16x32_bf16 v[92:95], v[138:141], v[224:227], v[92:95]
	v_mfma_f32_16x16x32_bf16 v[88:91], v[160:163], v[224:227], v[88:91]
	v_mfma_f32_16x16x32_bf16 v[76:79], v[138:141], v[232:235], v[76:79]
	v_mfma_f32_16x16x32_bf16 v[72:75], v[160:163], v[232:235], v[72:75]
	v_mfma_f32_16x16x32_bf16 v[124:127], v[156:159], v[212:215], v[124:127]
	v_mfma_f32_16x16x32_bf16 v[120:123], v[164:167], v[212:215], v[120:123]
	v_mfma_f32_16x16x32_bf16 v[108:111], v[156:159], v[220:223], v[108:111]
	v_mfma_f32_16x16x32_bf16 v[104:107], v[164:167], v[220:223], v[104:107]
	v_mfma_f32_16x16x32_bf16 v[92:95], v[156:159], v[228:231], v[92:95]
	v_mfma_f32_16x16x32_bf16 v[88:91], v[164:167], v[228:231], v[88:91]
	v_mfma_f32_16x16x32_bf16 v[76:79], v[156:159], v[236:239], v[76:79]
	v_mfma_f32_16x16x32_bf16 v[72:75], v[164:167], v[236:239], v[72:75]
	s_setprio 0
	s_setprio 1
	v_mfma_f32_16x16x32_bf16 v[116:119], v[168:171], v[208:211], v[116:119]
	v_mfma_f32_16x16x32_bf16 v[112:115], v[176:179], v[208:211], v[112:115]
	v_mfma_f32_16x16x32_bf16 v[100:103], v[168:171], v[216:219], v[100:103]
	v_mfma_f32_16x16x32_bf16 v[96:99], v[176:179], v[216:219], v[96:99]
	v_mfma_f32_16x16x32_bf16 v[84:87], v[168:171], v[224:227], v[84:87]
	v_mfma_f32_16x16x32_bf16 v[80:83], v[176:179], v[224:227], v[80:83]
	v_mfma_f32_16x16x32_bf16 v[68:71], v[168:171], v[232:235], v[68:71]
	v_mfma_f32_16x16x32_bf16 v[64:67], v[176:179], v[232:235], v[64:67]
	v_mfma_f32_16x16x32_bf16 v[116:119], v[172:175], v[212:215], v[116:119]
	v_mfma_f32_16x16x32_bf16 v[112:115], v[204:207], v[212:215], v[112:115]
	v_mfma_f32_16x16x32_bf16 v[100:103], v[172:175], v[220:223], v[100:103]
	v_mfma_f32_16x16x32_bf16 v[96:99], v[204:207], v[220:223], v[96:99]
	v_mfma_f32_16x16x32_bf16 v[84:87], v[172:175], v[228:231], v[84:87]
	v_mfma_f32_16x16x32_bf16 v[80:83], v[204:207], v[228:231], v[80:83]
	v_mfma_f32_16x16x32_bf16 v[68:71], v[172:175], v[236:239], v[68:71]
	v_mfma_f32_16x16x32_bf16 v[64:67], v[204:207], v[236:239], v[64:67]
	s_setprio 0
	s_barrier
	s_add_i32 s5, s84, s28
	v_lshl_add_u64 v[180:181], s[34:35], 0, v[144:145]
	s_mov_b32 m0, s5
	ds_read_b128 v[208:211], v155 offset:16384
	ds_read_b128 v[212:215], v155 offset:17408
	ds_read_b128 v[216:219], v155 offset:18432
	ds_read_b128 v[220:223], v155 offset:19456
	ds_read_b128 v[224:227], v155 offset:20480
	ds_read_b128 v[228:231], v155 offset:21504
	ds_read_b128 v[232:235], v155 offset:22528
	ds_read_b128 v[236:239], v155 offset:23552
	global_load_lds_dwordx4 v[180:181], off
	s_add_i32 m0, s5, 0x2000
	s_add_u32 s88, s34, 0x40000
	v_lshl_add_u64 v[240:241], s[34:35], 0, v[128:129]
	s_addc_u32 s89, s35, 0
	s_add_i32 s4, s4, s28
	global_load_lds_dwordx4 v[240:241], off
	v_lshl_add_u64 v[242:243], s[88:89], 0, v[144:145]
	s_mov_b32 m0, s4
	v_lshl_add_u64 v[244:245], s[64:65], 0, v[130:131]
	global_load_lds_dwordx4 v[242:243], off
	v_lshl_add_u64 v[242:243], s[88:89], 0, v[128:129]
	s_add_i32 m0, s4, 0x2000
	s_nop 0
	global_load_lds_dwordx4 v[242:243], off
	v_lshl_add_u64 v[242:243], s[64:65], 0, v[132:133]
	s_mov_b32 m0, s68
	s_nop 0
	global_load_lds_dwordx4 v[242:243], off
	s_mov_b32 m0, s69
	s_nop 0
	global_load_lds_dwordx4 v[244:245], off
	s_waitcnt vmcnt(8)
	s_waitcnt lgkmcnt(0)
	s_barrier
	s_setprio 1
	s_waitcnt lgkmcnt(0)
	v_mfma_f32_16x16x32_bf16 v[60:63], v[138:141], v[208:211], v[60:63]
	v_mfma_f32_16x16x32_bf16 v[56:59], v[160:163], v[208:211], v[56:59]
	v_mfma_f32_16x16x32_bf16 v[44:47], v[138:141], v[216:219], v[44:47]
	v_mfma_f32_16x16x32_bf16 v[40:43], v[160:163], v[216:219], v[40:43]
	v_mfma_f32_16x16x32_bf16 v[28:31], v[138:141], v[224:227], v[28:31]
	v_mfma_f32_16x16x32_bf16 v[24:27], v[160:163], v[224:227], v[24:27]
	v_mfma_f32_16x16x32_bf16 v[12:15], v[138:141], v[232:235], v[12:15]
	v_mfma_f32_16x16x32_bf16 v[8:11], v[160:163], v[232:235], v[8:11]
	v_mfma_f32_16x16x32_bf16 v[60:63], v[156:159], v[212:215], v[60:63]
	v_mfma_f32_16x16x32_bf16 v[56:59], v[164:167], v[212:215], v[56:59]
	v_mfma_f32_16x16x32_bf16 v[44:47], v[156:159], v[220:223], v[44:47]
	v_mfma_f32_16x16x32_bf16 v[40:43], v[164:167], v[220:223], v[40:43]
	v_mfma_f32_16x16x32_bf16 v[28:31], v[156:159], v[228:231], v[28:31]
	v_mfma_f32_16x16x32_bf16 v[24:27], v[164:167], v[228:231], v[24:27]
	v_mfma_f32_16x16x32_bf16 v[12:15], v[156:159], v[236:239], v[12:15]
	v_mfma_f32_16x16x32_bf16 v[8:11], v[164:167], v[236:239], v[8:11]
	s_setprio 0
	s_setprio 1
	v_mfma_f32_16x16x32_bf16 v[52:55], v[168:171], v[208:211], v[52:55]
	v_mfma_f32_16x16x32_bf16 v[48:51], v[176:179], v[208:211], v[48:51]
	v_mfma_f32_16x16x32_bf16 v[36:39], v[168:171], v[216:219], v[36:39]
	v_mfma_f32_16x16x32_bf16 v[32:35], v[176:179], v[216:219], v[32:35]
	v_mfma_f32_16x16x32_bf16 v[20:23], v[168:171], v[224:227], v[20:23]
	v_mfma_f32_16x16x32_bf16 v[16:19], v[176:179], v[224:227], v[16:19]
	v_mfma_f32_16x16x32_bf16 v[4:7], v[168:171], v[232:235], v[4:7]
	v_mfma_f32_16x16x32_bf16 v[0:3], v[176:179], v[232:235], v[0:3]
	v_mfma_f32_16x16x32_bf16 v[52:55], v[172:175], v[212:215], v[52:55]
	v_mfma_f32_16x16x32_bf16 v[48:51], v[204:207], v[212:215], v[48:51]
	v_mfma_f32_16x16x32_bf16 v[36:39], v[172:175], v[220:223], v[36:39]
	v_mfma_f32_16x16x32_bf16 v[32:35], v[204:207], v[220:223], v[32:35]
	v_mfma_f32_16x16x32_bf16 v[20:23], v[172:175], v[228:231], v[20:23]
	v_mfma_f32_16x16x32_bf16 v[16:19], v[204:207], v[228:231], v[16:19]
	v_mfma_f32_16x16x32_bf16 v[4:7], v[172:175], v[236:239], v[4:7]
	v_mfma_f32_16x16x32_bf16 v[0:3], v[204:207], v[236:239], v[0:3]
	s_setprio 0
	s_barrier
	s_add_i32 s4, 0, 0x18000
	s_add_i32 s5, 0, 0x1c000
	v_add_u32_e32 v164, s4, v143
	v_add_u32_e32 v202, s5, v143
	ds_read_b128 v[138:141], v164
	ds_read_b128 v[156:159], v164 offset:1024
	ds_read_b128 v[160:163], v164 offset:2048
	ds_read_b128 v[164:167], v164 offset:3072
	ds_read_b128 v[168:171], v202
	ds_read_b128 v[172:175], v202 offset:1024
	ds_read_b128 v[176:179], v202 offset:2048
	ds_read_b128 v[204:207], v202 offset:3072
	s_add_u32 s64, s64, 0x40000
	s_addc_u32 s65, s65, 0
	s_mov_b32 m0, s70
	v_lshl_add_u64 v[246:247], s[64:65], 0, v[132:133]
	ds_read_b128 v[208:211], v155 offset:32768
	ds_read_b128 v[212:215], v155 offset:33792
	ds_read_b128 v[216:219], v155 offset:34816
	ds_read_b128 v[220:223], v155 offset:35840
	ds_read_b128 v[224:227], v155 offset:36864
	ds_read_b128 v[228:231], v155 offset:37888
	ds_read_b128 v[232:235], v155 offset:38912
	ds_read_b128 v[236:239], v155 offset:39936
	global_load_lds_dwordx4 v[246:247], off
	v_lshl_add_u64 v[246:247], s[64:65], 0, v[130:131]
	s_mov_b32 m0, s71
	s_nop 0
	global_load_lds_dwordx4 v[246:247], off
	s_waitcnt vmcnt(8)
	s_waitcnt lgkmcnt(0)
	s_barrier
	s_setprio 1
	s_waitcnt lgkmcnt(0)
	v_mfma_f32_16x16x32_bf16 v[124:127], v[138:141], v[208:211], v[124:127]
	v_mfma_f32_16x16x32_bf16 v[120:123], v[160:163], v[208:211], v[120:123]
	v_mfma_f32_16x16x32_bf16 v[108:111], v[138:141], v[216:219], v[108:111]
	v_mfma_f32_16x16x32_bf16 v[104:107], v[160:163], v[216:219], v[104:107]
	v_mfma_f32_16x16x32_bf16 v[92:95], v[138:141], v[224:227], v[92:95]
	v_mfma_f32_16x16x32_bf16 v[88:91], v[160:163], v[224:227], v[88:91]
	v_mfma_f32_16x16x32_bf16 v[76:79], v[138:141], v[232:235], v[76:79]
	v_mfma_f32_16x16x32_bf16 v[72:75], v[160:163], v[232:235], v[72:75]
	v_mfma_f32_16x16x32_bf16 v[124:127], v[156:159], v[212:215], v[124:127]
	v_mfma_f32_16x16x32_bf16 v[120:123], v[164:167], v[212:215], v[120:123]
	v_mfma_f32_16x16x32_bf16 v[108:111], v[156:159], v[220:223], v[108:111]
	v_mfma_f32_16x16x32_bf16 v[104:107], v[164:167], v[220:223], v[104:107]
	v_mfma_f32_16x16x32_bf16 v[92:95], v[156:159], v[228:231], v[92:95]
	v_mfma_f32_16x16x32_bf16 v[88:91], v[164:167], v[228:231], v[88:91]
	v_mfma_f32_16x16x32_bf16 v[76:79], v[156:159], v[236:239], v[76:79]
	v_mfma_f32_16x16x32_bf16 v[72:75], v[164:167], v[236:239], v[72:75]
	s_setprio 0
	s_setprio 1
	v_mfma_f32_16x16x32_bf16 v[116:119], v[168:171], v[208:211], v[116:119]
	v_mfma_f32_16x16x32_bf16 v[112:115], v[176:179], v[208:211], v[112:115]
	v_mfma_f32_16x16x32_bf16 v[100:103], v[168:171], v[216:219], v[100:103]
	v_mfma_f32_16x16x32_bf16 v[96:99], v[176:179], v[216:219], v[96:99]
	v_mfma_f32_16x16x32_bf16 v[84:87], v[168:171], v[224:227], v[84:87]
	v_mfma_f32_16x16x32_bf16 v[80:83], v[176:179], v[224:227], v[80:83]
	v_mfma_f32_16x16x32_bf16 v[68:71], v[168:171], v[232:235], v[68:71]
	v_mfma_f32_16x16x32_bf16 v[64:67], v[176:179], v[232:235], v[64:67]
	v_mfma_f32_16x16x32_bf16 v[116:119], v[172:175], v[212:215], v[116:119]
	v_mfma_f32_16x16x32_bf16 v[112:115], v[204:207], v[212:215], v[112:115]
	v_mfma_f32_16x16x32_bf16 v[100:103], v[172:175], v[220:223], v[100:103]
	v_mfma_f32_16x16x32_bf16 v[96:99], v[204:207], v[220:223], v[96:99]
	v_mfma_f32_16x16x32_bf16 v[84:87], v[172:175], v[228:231], v[84:87]
	v_mfma_f32_16x16x32_bf16 v[80:83], v[204:207], v[228:231], v[80:83]
	v_mfma_f32_16x16x32_bf16 v[68:71], v[172:175], v[236:239], v[68:71]
	v_mfma_f32_16x16x32_bf16 v[64:67], v[204:207], v[236:239], v[64:67]
	s_setprio 0
	s_barrier
	s_add_i32 s4, s4, s28
	v_lshl_add_u64 v[180:181], v[180:181], 0, s[26:27]
	s_mov_b32 m0, s4
	ds_read_b128 v[208:211], v155 offset:49152
	ds_read_b128 v[212:215], v155 offset:50176
	ds_read_b128 v[216:219], v155 offset:51200
	ds_read_b128 v[220:223], v155 offset:52224
	ds_read_b128 v[224:227], v155 offset:53248
	ds_read_b128 v[228:231], v155 offset:54272
	ds_read_b128 v[232:235], v155 offset:55296
	ds_read_b128 v[236:239], v155 offset:56320
	global_load_lds_dwordx4 v[180:181], off
	s_add_i32 m0, s4, 0x2000
	s_add_u32 s34, s34, 0x40080
	v_lshl_add_u64 v[180:181], v[240:241], 0, s[26:27]
	s_addc_u32 s35, s35, 0
	s_add_i32 s4, s5, s28
	global_load_lds_dwordx4 v[180:181], off
	v_lshl_add_u64 v[180:181], s[34:35], 0, v[144:145]
	s_mov_b32 m0, s4
	s_nop 0
	global_load_lds_dwordx4 v[180:181], off
	v_lshl_add_u64 v[180:181], s[34:35], 0, v[128:129]
	s_add_i32 m0, s4, 0x2000
	s_nop 0
	global_load_lds_dwordx4 v[180:181], off
	v_lshl_add_u64 v[180:181], v[242:243], 0, s[26:27]
	s_mov_b32 m0, s72
	s_nop 0
	global_load_lds_dwordx4 v[180:181], off
	v_lshl_add_u64 v[180:181], v[244:245], 0, s[26:27]
	s_mov_b32 m0, s73
	s_nop 0
	global_load_lds_dwordx4 v[180:181], off
	s_waitcnt vmcnt(8)
	s_waitcnt lgkmcnt(0)
	s_barrier
	s_setprio 1
	s_waitcnt lgkmcnt(0)
	v_mfma_f32_16x16x32_bf16 v[60:63], v[138:141], v[208:211], v[60:63]
	v_mfma_f32_16x16x32_bf16 v[56:59], v[160:163], v[208:211], v[56:59]
	v_mfma_f32_16x16x32_bf16 v[44:47], v[138:141], v[216:219], v[44:47]
	v_mfma_f32_16x16x32_bf16 v[40:43], v[160:163], v[216:219], v[40:43]
	v_mfma_f32_16x16x32_bf16 v[28:31], v[138:141], v[224:227], v[28:31]
	v_mfma_f32_16x16x32_bf16 v[24:27], v[160:163], v[224:227], v[24:27]
	v_mfma_f32_16x16x32_bf16 v[12:15], v[138:141], v[232:235], v[12:15]
	v_mfma_f32_16x16x32_bf16 v[8:11], v[160:163], v[232:235], v[8:11]
	v_mfma_f32_16x16x32_bf16 v[60:63], v[156:159], v[212:215], v[60:63]
	v_mfma_f32_16x16x32_bf16 v[56:59], v[164:167], v[212:215], v[56:59]
	v_mfma_f32_16x16x32_bf16 v[44:47], v[156:159], v[220:223], v[44:47]
	v_mfma_f32_16x16x32_bf16 v[40:43], v[164:167], v[220:223], v[40:43]
	v_mfma_f32_16x16x32_bf16 v[28:31], v[156:159], v[228:231], v[28:31]
	v_mfma_f32_16x16x32_bf16 v[24:27], v[164:167], v[228:231], v[24:27]
	v_mfma_f32_16x16x32_bf16 v[12:15], v[156:159], v[236:239], v[12:15]
	v_mfma_f32_16x16x32_bf16 v[8:11], v[164:167], v[236:239], v[8:11]
	s_setprio 0
	s_setprio 1
	v_mfma_f32_16x16x32_bf16 v[52:55], v[168:171], v[208:211], v[52:55]
	v_mfma_f32_16x16x32_bf16 v[48:51], v[176:179], v[208:211], v[48:51]
	v_mfma_f32_16x16x32_bf16 v[36:39], v[168:171], v[216:219], v[36:39]
	v_mfma_f32_16x16x32_bf16 v[32:35], v[176:179], v[216:219], v[32:35]
	v_mfma_f32_16x16x32_bf16 v[20:23], v[168:171], v[224:227], v[20:23]
	v_mfma_f32_16x16x32_bf16 v[16:19], v[176:179], v[224:227], v[16:19]
	v_mfma_f32_16x16x32_bf16 v[4:7], v[168:171], v[232:235], v[4:7]
	v_mfma_f32_16x16x32_bf16 v[0:3], v[176:179], v[232:235], v[0:3]
	v_mfma_f32_16x16x32_bf16 v[52:55], v[172:175], v[212:215], v[52:55]
	v_mfma_f32_16x16x32_bf16 v[48:51], v[204:207], v[212:215], v[48:51]
	v_mfma_f32_16x16x32_bf16 v[36:39], v[172:175], v[220:223], v[36:39]
	v_mfma_f32_16x16x32_bf16 v[32:35], v[204:207], v[220:223], v[32:35]
	v_mfma_f32_16x16x32_bf16 v[20:23], v[172:175], v[228:231], v[20:23]
	v_mfma_f32_16x16x32_bf16 v[16:19], v[204:207], v[228:231], v[16:19]
	v_mfma_f32_16x16x32_bf16 v[4:7], v[172:175], v[236:239], v[4:7]
	v_mfma_f32_16x16x32_bf16 v[0:3], v[204:207], v[236:239], v[0:3]
	s_setprio 0
	s_barrier
	s_add_i32 s82, s82, 2
	s_add_u32 s62, s62, 0x100
	s_addc_u32 s63, s63, 0
	s_add_u32 s75, s75, 0x100
	s_addc_u32 s79, s79, 0
	s_cmp_gt_u32 s82, 13
	s_cbranch_scc0 .LBB0_311
	v_lshl_add_u32 v140, s2, 8, v142
	v_ashrrev_i32_e32 v141, 31, v140
	v_lshl_add_u64 v[156:157], v[140:141], 4, s[48:49]
	global_load_dwordx4 v[208:211], v[156:157], off
	global_load_dwordx4 v[212:215], v[156:157], off offset:256
	global_load_dwordx4 v[216:219], v[156:157], off offset:512
	global_load_dwordx4 v[220:223], v[156:157], off offset:768
	global_load_dwordx4 v[224:227], v[156:157], off offset:2048
	global_load_dwordx4 v[228:231], v[156:157], off offset:2304
	global_load_dwordx4 v[232:235], v[156:157], off offset:2560
	global_load_dwordx4 v[236:239], v[156:157], off offset:2816
	s_and_b64 vcc, exec, s[50:51]
	s_cbranch_vccz .LBB0_314
	s_barrier
.LBB0_314:
	v_lshl_or_b32 v164, s3, 8, v154
	v_mov_b32_e32 v176, 0xbfb8aa3b
	v_ashrrev_i32_e32 v164, 1, v164
	v_ashrrev_i32_e32 v165, 31, v164
	v_mov_b32_e32 v177, 0xbfb8aa3b
	v_lshl_add_u64 v[138:139], v[164:165], 1, s[46:47]
	s_waitcnt vmcnt(0)
	v_add_f32_e32 v208, v209, v208
	v_add_f32_e32 v212, v213, v212
	v_add_f32_e32 v216, v217, v216
	v_add_f32_e32 v220, v221, v220
	v_add_f32_e32 v224, v225, v224
	v_add_f32_e32 v228, v229, v228
	v_add_f32_e32 v232, v233, v232
	v_add_f32_e32 v236, v237, v236
	v_add_f32_e32 v210, v210, v211
	v_add_f32_e32 v214, v214, v215
	v_add_f32_e32 v218, v218, v219
	v_add_f32_e32 v222, v222, v223
	v_add_f32_e32 v226, v226, v227
	v_add_f32_e32 v230, v230, v231
	v_add_f32_e32 v234, v234, v235
	v_add_f32_e32 v238, v238, v239
	v_add_f32_e32 v208, v208, v210
	v_add_f32_e32 v212, v212, v214
	v_add_f32_e32 v216, v216, v218
	v_add_f32_e32 v220, v220, v222
	v_add_f32_e32 v224, v224, v226
	v_add_f32_e32 v228, v228, v230
	v_add_f32_e32 v232, v232, v234
	v_add_f32_e32 v236, v236, v238
	v_fmamk_f32 v208, v208, 0x3a800000, v184
	v_fmamk_f32 v212, v212, 0x3a800000, v184
	v_fmamk_f32 v216, v216, 0x3a800000, v184
	v_fmamk_f32 v220, v220, 0x3a800000, v184
	v_fmamk_f32 v224, v224, 0x3a800000, v184
	v_fmamk_f32 v228, v228, 0x3a800000, v184
	v_fmamk_f32 v232, v232, 0x3a800000, v184
	v_fmamk_f32 v236, v236, 0x3a800000, v184
	v_rsq_f32_e32 v160, v208
	v_rsq_f32_e32 v162, v212
	v_rsq_f32_e32 v164, v216
	v_rsq_f32_e32 v166, v220
	v_rsq_f32_e32 v168, v224
	v_rsq_f32_e32 v170, v228
	v_rsq_f32_e32 v172, v232
	v_rsq_f32_e32 v174, v236
	v_pk_mul_f32 v[124:125], v[124:125], v[160:161] op_sel_hi:[1,0]
	v_pk_mul_f32 v[126:127], v[126:127], v[160:161] op_sel_hi:[1,0]
	v_pk_mul_f32 v[116:117], v[116:117], v[160:161] op_sel_hi:[1,0]
	v_pk_mul_f32 v[118:119], v[118:119], v[160:161] op_sel_hi:[1,0]
	v_pk_mul_f32 v[120:121], v[120:121], v[160:161] op_sel_hi:[1,0]
	v_pk_mul_f32 v[122:123], v[122:123], v[160:161] op_sel_hi:[1,0]
	v_pk_mul_f32 v[112:113], v[112:113], v[160:161] op_sel_hi:[1,0]
	v_pk_mul_f32 v[114:115], v[114:115], v[160:161] op_sel_hi:[1,0]
	v_pk_mul_f32 v[232:233], v[124:125], v[176:177] op_sel_hi:[1,0]
	v_pk_mul_f32 v[234:235], v[126:127], v[176:177] op_sel_hi:[1,0]
	v_pk_mul_f32 v[236:237], v[116:117], v[176:177] op_sel_hi:[1,0]
	v_pk_mul_f32 v[238:239], v[118:119], v[176:177] op_sel_hi:[1,0]
	v_mad_i64_i32 v[216:217], s[2:3], v140, s78, v[138:139]
	v_exp_f32_e32 v232, v232
	v_exp_f32_e32 v233, v233
	v_exp_f32_e32 v234, v234
	v_exp_f32_e32 v235, v235
	v_exp_f32_e32 v236, v236
	v_exp_f32_e32 v237, v237
	v_exp_f32_e32 v238, v238
	v_exp_f32_e32 v239, v239
	v_pk_add_f32 v[232:233], v[232:233], 1.0 op_sel_hi:[1,0]
	v_pk_add_f32 v[234:235], v[234:235], 1.0 op_sel_hi:[1,0]
	v_pk_add_f32 v[236:237], v[236:237], 1.0 op_sel_hi:[1,0]
	v_pk_add_f32 v[238:239], v[238:239], 1.0 op_sel_hi:[1,0]
	v_rcp_f32_e32 v232, v232
	v_rcp_f32_e32 v233, v233
	v_rcp_f32_e32 v234, v234
	v_rcp_f32_e32 v235, v235
	v_rcp_f32_e32 v236, v236
	v_rcp_f32_e32 v237, v237
	v_rcp_f32_e32 v238, v238
	v_rcp_f32_e32 v239, v239
	v_pk_mul_f32 v[232:233], v[124:125], v[232:233]
	v_pk_mul_f32 v[234:235], v[126:127], v[234:235]
	v_pk_mul_f32 v[236:237], v[116:117], v[236:237]
	v_pk_mul_f32 v[238:239], v[118:119], v[238:239]
	v_pk_mul_f32 v[232:233], v[120:121], v[232:233]
	v_pk_mul_f32 v[234:235], v[122:123], v[234:235]
	v_pk_mul_f32 v[236:237], v[112:113], v[236:237]
	v_pk_mul_f32 v[238:239], v[114:115], v[238:239]
	v_cvt_pk_bf16_f32 v224, v232, v233
	v_cvt_pk_bf16_f32 v225, v234, v235
	v_cvt_pk_bf16_f32 v226, v236, v237
	v_cvt_pk_bf16_f32 v227, v238, v239
	global_store_dwordx2 v[216:217], v[224:225], off
	global_store_dwordx2 v[216:217], v[226:227], off offset:128
	v_pk_mul_f32 v[108:109], v[108:109], v[162:163] op_sel_hi:[1,0]
	v_pk_mul_f32 v[110:111], v[110:111], v[162:163] op_sel_hi:[1,0]
	v_pk_mul_f32 v[100:101], v[100:101], v[162:163] op_sel_hi:[1,0]
	v_pk_mul_f32 v[102:103], v[102:103], v[162:163] op_sel_hi:[1,0]
	v_pk_mul_f32 v[104:105], v[104:105], v[162:163] op_sel_hi:[1,0]
	v_pk_mul_f32 v[106:107], v[106:107], v[162:163] op_sel_hi:[1,0]
	v_pk_mul_f32 v[96:97], v[96:97], v[162:163] op_sel_hi:[1,0]
	v_pk_mul_f32 v[98:99], v[98:99], v[162:163] op_sel_hi:[1,0]
	v_add_u32_e32 v141, 0x10, v140
	v_pk_mul_f32 v[232:233], v[108:109], v[176:177] op_sel_hi:[1,0]
	v_pk_mul_f32 v[234:235], v[110:111], v[176:177] op_sel_hi:[1,0]
	v_pk_mul_f32 v[236:237], v[100:101], v[176:177] op_sel_hi:[1,0]
	v_pk_mul_f32 v[238:239], v[102:103], v[176:177] op_sel_hi:[1,0]
	v_mad_i64_i32 v[218:219], s[2:3], v141, s78, v[138:139]
	v_exp_f32_e32 v232, v232
	v_exp_f32_e32 v233, v233
	v_exp_f32_e32 v234, v234
	v_exp_f32_e32 v235, v235
	v_exp_f32_e32 v236, v236
	v_exp_f32_e32 v237, v237
	v_exp_f32_e32 v238, v238
	v_exp_f32_e32 v239, v239
	v_pk_add_f32 v[232:233], v[232:233], 1.0 op_sel_hi:[1,0]
	v_pk_add_f32 v[234:235], v[234:235], 1.0 op_sel_hi:[1,0]
	v_pk_add_f32 v[236:237], v[236:237], 1.0 op_sel_hi:[1,0]
	v_pk_add_f32 v[238:239], v[238:239], 1.0 op_sel_hi:[1,0]
	v_rcp_f32_e32 v232, v232
	v_rcp_f32_e32 v233, v233
	v_rcp_f32_e32 v234, v234
	v_rcp_f32_e32 v235, v235
	v_rcp_f32_e32 v236, v236
	v_rcp_f32_e32 v237, v237
	v_rcp_f32_e32 v238, v238
	v_rcp_f32_e32 v239, v239
	v_pk_mul_f32 v[232:233], v[108:109], v[232:233]
	v_pk_mul_f32 v[234:235], v[110:111], v[234:235]
	v_pk_mul_f32 v[236:237], v[100:101], v[236:237]
	v_pk_mul_f32 v[238:239], v[102:103], v[238:239]
	v_pk_mul_f32 v[232:233], v[104:105], v[232:233]
	v_pk_mul_f32 v[234:235], v[106:107], v[234:235]
	v_pk_mul_f32 v[236:237], v[96:97], v[236:237]
	v_pk_mul_f32 v[238:239], v[98:99], v[238:239]
	v_cvt_pk_bf16_f32 v228, v232, v233
	v_cvt_pk_bf16_f32 v229, v234, v235
	v_cvt_pk_bf16_f32 v230, v236, v237
	v_cvt_pk_bf16_f32 v231, v238, v239
	global_store_dwordx2 v[218:219], v[228:229], off
	global_store_dwordx2 v[218:219], v[230:231], off offset:128
	v_pk_mul_f32 v[92:93], v[92:93], v[164:165] op_sel_hi:[1,0]
	v_pk_mul_f32 v[94:95], v[94:95], v[164:165] op_sel_hi:[1,0]
	v_pk_mul_f32 v[84:85], v[84:85], v[164:165] op_sel_hi:[1,0]
	v_pk_mul_f32 v[86:87], v[86:87], v[164:165] op_sel_hi:[1,0]
	v_pk_mul_f32 v[88:89], v[88:89], v[164:165] op_sel_hi:[1,0]
	v_pk_mul_f32 v[90:91], v[90:91], v[164:165] op_sel_hi:[1,0]
	v_pk_mul_f32 v[80:81], v[80:81], v[164:165] op_sel_hi:[1,0]
	v_pk_mul_f32 v[82:83], v[82:83], v[164:165] op_sel_hi:[1,0]
	v_add_u32_e32 v141, 0x20, v140
	v_pk_mul_f32 v[232:233], v[92:93], v[176:177] op_sel_hi:[1,0]
	v_pk_mul_f32 v[234:235], v[94:95], v[176:177] op_sel_hi:[1,0]
	v_pk_mul_f32 v[236:237], v[84:85], v[176:177] op_sel_hi:[1,0]
	v_pk_mul_f32 v[238:239], v[86:87], v[176:177] op_sel_hi:[1,0]
	v_mad_i64_i32 v[220:221], s[2:3], v141, s78, v[138:139]
	v_exp_f32_e32 v232, v232
	v_exp_f32_e32 v233, v233
	v_exp_f32_e32 v234, v234
	v_exp_f32_e32 v235, v235
	v_exp_f32_e32 v236, v236
	v_exp_f32_e32 v237, v237
	v_exp_f32_e32 v238, v238
	v_exp_f32_e32 v239, v239
	v_pk_add_f32 v[232:233], v[232:233], 1.0 op_sel_hi:[1,0]
	v_pk_add_f32 v[234:235], v[234:235], 1.0 op_sel_hi:[1,0]
	v_pk_add_f32 v[236:237], v[236:237], 1.0 op_sel_hi:[1,0]
	v_pk_add_f32 v[238:239], v[238:239], 1.0 op_sel_hi:[1,0]
	v_rcp_f32_e32 v232, v232
	v_rcp_f32_e32 v233, v233
	v_rcp_f32_e32 v234, v234
	v_rcp_f32_e32 v235, v235
	v_rcp_f32_e32 v236, v236
	v_rcp_f32_e32 v237, v237
	v_rcp_f32_e32 v238, v238
	v_rcp_f32_e32 v239, v239
	v_pk_mul_f32 v[232:233], v[92:93], v[232:233]
	v_pk_mul_f32 v[234:235], v[94:95], v[234:235]
	v_pk_mul_f32 v[236:237], v[84:85], v[236:237]
	v_pk_mul_f32 v[238:239], v[86:87], v[238:239]
	v_pk_mul_f32 v[232:233], v[88:89], v[232:233]
	v_pk_mul_f32 v[234:235], v[90:91], v[234:235]
	v_pk_mul_f32 v[236:237], v[80:81], v[236:237]
	v_pk_mul_f32 v[238:239], v[82:83], v[238:239]
	v_cvt_pk_bf16_f32 v224, v232, v233
	v_cvt_pk_bf16_f32 v225, v234, v235
	v_cvt_pk_bf16_f32 v226, v236, v237
	v_cvt_pk_bf16_f32 v227, v238, v239
	global_store_dwordx2 v[220:221], v[224:225], off
	global_store_dwordx2 v[220:221], v[226:227], off offset:128
	v_pk_mul_f32 v[76:77], v[76:77], v[166:167] op_sel_hi:[1,0]
	v_pk_mul_f32 v[78:79], v[78:79], v[166:167] op_sel_hi:[1,0]
	v_pk_mul_f32 v[68:69], v[68:69], v[166:167] op_sel_hi:[1,0]
	v_pk_mul_f32 v[70:71], v[70:71], v[166:167] op_sel_hi:[1,0]
	v_pk_mul_f32 v[72:73], v[72:73], v[166:167] op_sel_hi:[1,0]
	v_pk_mul_f32 v[74:75], v[74:75], v[166:167] op_sel_hi:[1,0]
	v_pk_mul_f32 v[64:65], v[64:65], v[166:167] op_sel_hi:[1,0]
	v_pk_mul_f32 v[66:67], v[66:67], v[166:167] op_sel_hi:[1,0]
	v_add_u32_e32 v141, 0x30, v140
	v_pk_mul_f32 v[232:233], v[76:77], v[176:177] op_sel_hi:[1,0]
	v_pk_mul_f32 v[234:235], v[78:79], v[176:177] op_sel_hi:[1,0]
	v_pk_mul_f32 v[236:237], v[68:69], v[176:177] op_sel_hi:[1,0]
	v_pk_mul_f32 v[238:239], v[70:71], v[176:177] op_sel_hi:[1,0]
	v_mad_i64_i32 v[222:223], s[2:3], v141, s78, v[138:139]
	v_exp_f32_e32 v232, v232
	v_exp_f32_e32 v233, v233
	v_exp_f32_e32 v234, v234
	v_exp_f32_e32 v235, v235
	v_exp_f32_e32 v236, v236
	v_exp_f32_e32 v237, v237
	v_exp_f32_e32 v238, v238
	v_exp_f32_e32 v239, v239
	v_pk_add_f32 v[232:233], v[232:233], 1.0 op_sel_hi:[1,0]
	v_pk_add_f32 v[234:235], v[234:235], 1.0 op_sel_hi:[1,0]
	v_pk_add_f32 v[236:237], v[236:237], 1.0 op_sel_hi:[1,0]
	v_pk_add_f32 v[238:239], v[238:239], 1.0 op_sel_hi:[1,0]
	v_rcp_f32_e32 v232, v232
	v_rcp_f32_e32 v233, v233
	v_rcp_f32_e32 v234, v234
	v_rcp_f32_e32 v235, v235
	v_rcp_f32_e32 v236, v236
	v_rcp_f32_e32 v237, v237
	v_rcp_f32_e32 v238, v238
	v_rcp_f32_e32 v239, v239
	v_pk_mul_f32 v[232:233], v[76:77], v[232:233]
	v_pk_mul_f32 v[234:235], v[78:79], v[234:235]
	v_pk_mul_f32 v[236:237], v[68:69], v[236:237]
	v_pk_mul_f32 v[238:239], v[70:71], v[238:239]
	v_pk_mul_f32 v[232:233], v[72:73], v[232:233]
	v_pk_mul_f32 v[234:235], v[74:75], v[234:235]
	v_pk_mul_f32 v[236:237], v[64:65], v[236:237]
	v_pk_mul_f32 v[238:239], v[66:67], v[238:239]
	v_cvt_pk_bf16_f32 v228, v232, v233
	v_cvt_pk_bf16_f32 v229, v234, v235
	v_cvt_pk_bf16_f32 v230, v236, v237
	v_cvt_pk_bf16_f32 v231, v238, v239
	global_store_dwordx2 v[222:223], v[228:229], off
	global_store_dwordx2 v[222:223], v[230:231], off offset:128
	v_pk_mul_f32 v[60:61], v[60:61], v[168:169] op_sel_hi:[1,0]
	v_pk_mul_f32 v[62:63], v[62:63], v[168:169] op_sel_hi:[1,0]
	v_pk_mul_f32 v[52:53], v[52:53], v[168:169] op_sel_hi:[1,0]
	v_pk_mul_f32 v[54:55], v[54:55], v[168:169] op_sel_hi:[1,0]
	v_pk_mul_f32 v[56:57], v[56:57], v[168:169] op_sel_hi:[1,0]
	v_pk_mul_f32 v[58:59], v[58:59], v[168:169] op_sel_hi:[1,0]
	v_pk_mul_f32 v[48:49], v[48:49], v[168:169] op_sel_hi:[1,0]
	v_pk_mul_f32 v[50:51], v[50:51], v[168:169] op_sel_hi:[1,0]
	v_add_u32_e32 v141, 0x80, v140
	v_pk_mul_f32 v[232:233], v[60:61], v[176:177] op_sel_hi:[1,0]
	v_pk_mul_f32 v[234:235], v[62:63], v[176:177] op_sel_hi:[1,0]
	v_pk_mul_f32 v[236:237], v[52:53], v[176:177] op_sel_hi:[1,0]
	v_pk_mul_f32 v[238:239], v[54:55], v[176:177] op_sel_hi:[1,0]
	v_mad_i64_i32 v[216:217], s[2:3], v141, s78, v[138:139]
	v_exp_f32_e32 v232, v232
	v_exp_f32_e32 v233, v233
	v_exp_f32_e32 v234, v234
	v_exp_f32_e32 v235, v235
	v_exp_f32_e32 v236, v236
	v_exp_f32_e32 v237, v237
	v_exp_f32_e32 v238, v238
	v_exp_f32_e32 v239, v239
	v_pk_add_f32 v[232:233], v[232:233], 1.0 op_sel_hi:[1,0]
	v_pk_add_f32 v[234:235], v[234:235], 1.0 op_sel_hi:[1,0]
	v_pk_add_f32 v[236:237], v[236:237], 1.0 op_sel_hi:[1,0]
	v_pk_add_f32 v[238:239], v[238:239], 1.0 op_sel_hi:[1,0]
	v_rcp_f32_e32 v232, v232
	v_rcp_f32_e32 v233, v233
	v_rcp_f32_e32 v234, v234
	v_rcp_f32_e32 v235, v235
	v_rcp_f32_e32 v236, v236
	v_rcp_f32_e32 v237, v237
	v_rcp_f32_e32 v238, v238
	v_rcp_f32_e32 v239, v239
	v_pk_mul_f32 v[232:233], v[60:61], v[232:233]
	v_pk_mul_f32 v[234:235], v[62:63], v[234:235]
	v_pk_mul_f32 v[236:237], v[52:53], v[236:237]
	v_pk_mul_f32 v[238:239], v[54:55], v[238:239]
	v_pk_mul_f32 v[232:233], v[56:57], v[232:233]
	v_pk_mul_f32 v[234:235], v[58:59], v[234:235]
	v_pk_mul_f32 v[236:237], v[48:49], v[236:237]
	v_pk_mul_f32 v[238:239], v[50:51], v[238:239]
	v_cvt_pk_bf16_f32 v224, v232, v233
	v_cvt_pk_bf16_f32 v225, v234, v235
	v_cvt_pk_bf16_f32 v226, v236, v237
	v_cvt_pk_bf16_f32 v227, v238, v239
	global_store_dwordx2 v[216:217], v[224:225], off
	global_store_dwordx2 v[216:217], v[226:227], off offset:128
	v_pk_mul_f32 v[44:45], v[44:45], v[170:171] op_sel_hi:[1,0]
	v_pk_mul_f32 v[46:47], v[46:47], v[170:171] op_sel_hi:[1,0]
	v_pk_mul_f32 v[36:37], v[36:37], v[170:171] op_sel_hi:[1,0]
	v_pk_mul_f32 v[38:39], v[38:39], v[170:171] op_sel_hi:[1,0]
	v_pk_mul_f32 v[40:41], v[40:41], v[170:171] op_sel_hi:[1,0]
	v_pk_mul_f32 v[42:43], v[42:43], v[170:171] op_sel_hi:[1,0]
	v_pk_mul_f32 v[32:33], v[32:33], v[170:171] op_sel_hi:[1,0]
	v_pk_mul_f32 v[34:35], v[34:35], v[170:171] op_sel_hi:[1,0]
	v_add_u32_e32 v141, 0x90, v140
	v_pk_mul_f32 v[232:233], v[44:45], v[176:177] op_sel_hi:[1,0]
	v_pk_mul_f32 v[234:235], v[46:47], v[176:177] op_sel_hi:[1,0]
	v_pk_mul_f32 v[236:237], v[36:37], v[176:177] op_sel_hi:[1,0]
	v_pk_mul_f32 v[238:239], v[38:39], v[176:177] op_sel_hi:[1,0]
	v_mad_i64_i32 v[218:219], s[2:3], v141, s78, v[138:139]
	v_exp_f32_e32 v232, v232
	v_exp_f32_e32 v233, v233
	v_exp_f32_e32 v234, v234
	v_exp_f32_e32 v235, v235
	v_exp_f32_e32 v236, v236
	v_exp_f32_e32 v237, v237
	v_exp_f32_e32 v238, v238
	v_exp_f32_e32 v239, v239
	v_pk_add_f32 v[232:233], v[232:233], 1.0 op_sel_hi:[1,0]
	v_pk_add_f32 v[234:235], v[234:235], 1.0 op_sel_hi:[1,0]
	v_pk_add_f32 v[236:237], v[236:237], 1.0 op_sel_hi:[1,0]
	v_pk_add_f32 v[238:239], v[238:239], 1.0 op_sel_hi:[1,0]
	v_rcp_f32_e32 v232, v232
	v_rcp_f32_e32 v233, v233
	v_rcp_f32_e32 v234, v234
	v_rcp_f32_e32 v235, v235
	v_rcp_f32_e32 v236, v236
	v_rcp_f32_e32 v237, v237
	v_rcp_f32_e32 v238, v238
	v_rcp_f32_e32 v239, v239
	v_pk_mul_f32 v[232:233], v[44:45], v[232:233]
	v_pk_mul_f32 v[234:235], v[46:47], v[234:235]
	v_pk_mul_f32 v[236:237], v[36:37], v[236:237]
	v_pk_mul_f32 v[238:239], v[38:39], v[238:239]
	v_pk_mul_f32 v[232:233], v[40:41], v[232:233]
	v_pk_mul_f32 v[234:235], v[42:43], v[234:235]
	v_pk_mul_f32 v[236:237], v[32:33], v[236:237]
	v_pk_mul_f32 v[238:239], v[34:35], v[238:239]
	v_cvt_pk_bf16_f32 v228, v232, v233
	v_cvt_pk_bf16_f32 v229, v234, v235
	v_cvt_pk_bf16_f32 v230, v236, v237
	v_cvt_pk_bf16_f32 v231, v238, v239
	global_store_dwordx2 v[218:219], v[228:229], off
	global_store_dwordx2 v[218:219], v[230:231], off offset:128
	v_pk_mul_f32 v[28:29], v[28:29], v[172:173] op_sel_hi:[1,0]
	v_pk_mul_f32 v[30:31], v[30:31], v[172:173] op_sel_hi:[1,0]
	v_pk_mul_f32 v[20:21], v[20:21], v[172:173] op_sel_hi:[1,0]
	v_pk_mul_f32 v[22:23], v[22:23], v[172:173] op_sel_hi:[1,0]
	v_pk_mul_f32 v[24:25], v[24:25], v[172:173] op_sel_hi:[1,0]
	v_pk_mul_f32 v[26:27], v[26:27], v[172:173] op_sel_hi:[1,0]
	v_pk_mul_f32 v[16:17], v[16:17], v[172:173] op_sel_hi:[1,0]
	v_pk_mul_f32 v[18:19], v[18:19], v[172:173] op_sel_hi:[1,0]
	v_add_u32_e32 v141, 0xa0, v140
	v_pk_mul_f32 v[232:233], v[28:29], v[176:177] op_sel_hi:[1,0]
	v_pk_mul_f32 v[234:235], v[30:31], v[176:177] op_sel_hi:[1,0]
	v_pk_mul_f32 v[236:237], v[20:21], v[176:177] op_sel_hi:[1,0]
	v_pk_mul_f32 v[238:239], v[22:23], v[176:177] op_sel_hi:[1,0]
	v_mad_i64_i32 v[220:221], s[2:3], v141, s78, v[138:139]
	v_exp_f32_e32 v232, v232
	v_exp_f32_e32 v233, v233
	v_exp_f32_e32 v234, v234
	v_exp_f32_e32 v235, v235
	v_exp_f32_e32 v236, v236
	v_exp_f32_e32 v237, v237
	v_exp_f32_e32 v238, v238
	v_exp_f32_e32 v239, v239
	v_pk_add_f32 v[232:233], v[232:233], 1.0 op_sel_hi:[1,0]
	v_pk_add_f32 v[234:235], v[234:235], 1.0 op_sel_hi:[1,0]
	v_pk_add_f32 v[236:237], v[236:237], 1.0 op_sel_hi:[1,0]
	v_pk_add_f32 v[238:239], v[238:239], 1.0 op_sel_hi:[1,0]
	v_rcp_f32_e32 v232, v232
	v_rcp_f32_e32 v233, v233
	v_rcp_f32_e32 v234, v234
	v_rcp_f32_e32 v235, v235
	v_rcp_f32_e32 v236, v236
	v_rcp_f32_e32 v237, v237
	v_rcp_f32_e32 v238, v238
	v_rcp_f32_e32 v239, v239
	v_pk_mul_f32 v[232:233], v[28:29], v[232:233]
	v_pk_mul_f32 v[234:235], v[30:31], v[234:235]
	v_pk_mul_f32 v[236:237], v[20:21], v[236:237]
	v_pk_mul_f32 v[238:239], v[22:23], v[238:239]
	v_pk_mul_f32 v[232:233], v[24:25], v[232:233]
	v_pk_mul_f32 v[234:235], v[26:27], v[234:235]
	v_pk_mul_f32 v[236:237], v[16:17], v[236:237]
	v_pk_mul_f32 v[238:239], v[18:19], v[238:239]
	v_cvt_pk_bf16_f32 v224, v232, v233
	v_cvt_pk_bf16_f32 v225, v234, v235
	v_cvt_pk_bf16_f32 v226, v236, v237
	v_cvt_pk_bf16_f32 v227, v238, v239
	global_store_dwordx2 v[220:221], v[224:225], off
	global_store_dwordx2 v[220:221], v[226:227], off offset:128
	v_pk_mul_f32 v[12:13], v[12:13], v[174:175] op_sel_hi:[1,0]
	v_pk_mul_f32 v[14:15], v[14:15], v[174:175] op_sel_hi:[1,0]
	v_pk_mul_f32 v[4:5], v[4:5], v[174:175] op_sel_hi:[1,0]
	v_pk_mul_f32 v[6:7], v[6:7], v[174:175] op_sel_hi:[1,0]
	v_pk_mul_f32 v[8:9], v[8:9], v[174:175] op_sel_hi:[1,0]
	v_pk_mul_f32 v[10:11], v[10:11], v[174:175] op_sel_hi:[1,0]
	v_pk_mul_f32 v[0:1], v[0:1], v[174:175] op_sel_hi:[1,0]
	v_pk_mul_f32 v[2:3], v[2:3], v[174:175] op_sel_hi:[1,0]
	v_add_u32_e32 v141, 0xb0, v140
	v_pk_mul_f32 v[232:233], v[12:13], v[176:177] op_sel_hi:[1,0]
	v_pk_mul_f32 v[234:235], v[14:15], v[176:177] op_sel_hi:[1,0]
	v_pk_mul_f32 v[236:237], v[4:5], v[176:177] op_sel_hi:[1,0]
	v_pk_mul_f32 v[238:239], v[6:7], v[176:177] op_sel_hi:[1,0]
	v_mad_i64_i32 v[222:223], s[2:3], v141, s78, v[138:139]
	v_exp_f32_e32 v232, v232
	v_exp_f32_e32 v233, v233
	v_exp_f32_e32 v234, v234
	v_exp_f32_e32 v235, v235
	v_exp_f32_e32 v236, v236
	v_exp_f32_e32 v237, v237
	v_exp_f32_e32 v238, v238
	v_exp_f32_e32 v239, v239
	v_pk_add_f32 v[232:233], v[232:233], 1.0 op_sel_hi:[1,0]
	v_pk_add_f32 v[234:235], v[234:235], 1.0 op_sel_hi:[1,0]
	v_pk_add_f32 v[236:237], v[236:237], 1.0 op_sel_hi:[1,0]
	v_pk_add_f32 v[238:239], v[238:239], 1.0 op_sel_hi:[1,0]
	v_rcp_f32_e32 v232, v232
	v_rcp_f32_e32 v233, v233
	v_rcp_f32_e32 v234, v234
	v_rcp_f32_e32 v235, v235
	v_rcp_f32_e32 v236, v236
	v_rcp_f32_e32 v237, v237
	v_rcp_f32_e32 v238, v238
	v_rcp_f32_e32 v239, v239
	v_pk_mul_f32 v[232:233], v[12:13], v[232:233]
	v_pk_mul_f32 v[234:235], v[14:15], v[234:235]
	v_pk_mul_f32 v[236:237], v[4:5], v[236:237]
	v_pk_mul_f32 v[238:239], v[6:7], v[238:239]
	v_pk_mul_f32 v[232:233], v[8:9], v[232:233]
	v_pk_mul_f32 v[234:235], v[10:11], v[234:235]
	v_pk_mul_f32 v[236:237], v[0:1], v[236:237]
	v_pk_mul_f32 v[238:239], v[2:3], v[238:239]
	v_cvt_pk_bf16_f32 v228, v232, v233
	v_cvt_pk_bf16_f32 v229, v234, v235
	v_cvt_pk_bf16_f32 v230, v236, v237
	v_cvt_pk_bf16_f32 v231, v238, v239
	global_store_dwordx2 v[222:223], v[228:229], off
	global_store_dwordx2 v[222:223], v[230:231], off offset:128
	s_mov_b64 s[2:3], -1
	s_andn2_b64 vcc, exec, s[38:39]
	s_cbranch_vccnz .LBB0_307
	s_andn2_b64 vcc, exec, s[40:41]
	s_cbranch_vccnz .LBB0_306
	s_barrier
	s_branch .LBB0_306

.LBB0_1305:
	s_add_u32 s4, s2, 0xfffc0080
	s_addc_u32 s5, s3, -1
	s_add_i32 s74, 0, 0x10000
	s_cmp_eq_u32 s73, 12
	s_cselect_b32 s61, s36, s5
	s_cselect_b32 s60, s51, s4
	s_cselect_b32 s35, s49, s72
	s_cselect_b32 s34, s70, s71
	s_add_i32 s75, 0, 0x14000
	v_add_u32_e32 v164, s74, v143
	v_add_u32_e32 v180, s75, v143
	ds_read_b128 v[138:141], v164
	ds_read_b128 v[156:159], v164 offset:1024
	ds_read_b128 v[160:163], v164 offset:2048
	ds_read_b128 v[164:167], v164 offset:3072
	ds_read_b128 v[168:171], v180
	ds_read_b128 v[172:175], v180 offset:1024
	ds_read_b128 v[176:179], v180 offset:2048
	ds_read_b128 v[204:207], v180 offset:3072
	v_lshl_add_u64 v[180:181], s[2:3], 0, v[134:135]
	s_add_i32 m0, s59, 0xc000
	ds_read_b128 v[208:211], v155
	ds_read_b128 v[212:215], v155 offset:1024
	ds_read_b128 v[216:219], v155 offset:2048
	ds_read_b128 v[220:223], v155 offset:3072
	ds_read_b128 v[224:227], v155 offset:4096
	ds_read_b128 v[228:231], v155 offset:5120
	ds_read_b128 v[232:235], v155 offset:6144
	ds_read_b128 v[236:239], v155 offset:7168
	global_load_lds_dwordx4 v[180:181], off
	v_lshl_add_u64 v[180:181], s[2:3], 0, v[136:137]
	s_add_i32 m0, s59, 0xe000
	s_nop 0
	global_load_lds_dwordx4 v[180:181], off
	s_waitcnt vmcnt(8)
	s_waitcnt lgkmcnt(0)
	s_barrier
	s_setprio 1
	s_waitcnt lgkmcnt(0)
	v_mfma_f32_16x16x32_bf16 v[124:127], v[138:141], v[208:211], v[124:127]
	v_mfma_f32_16x16x32_bf16 v[120:123], v[160:163], v[208:211], v[120:123]
	v_mfma_f32_16x16x32_bf16 v[108:111], v[138:141], v[216:219], v[108:111]
	v_mfma_f32_16x16x32_bf16 v[104:107], v[160:163], v[216:219], v[104:107]
	v_mfma_f32_16x16x32_bf16 v[92:95], v[138:141], v[224:227], v[92:95]
	v_mfma_f32_16x16x32_bf16 v[88:91], v[160:163], v[224:227], v[88:91]
	v_mfma_f32_16x16x32_bf16 v[76:79], v[138:141], v[232:235], v[76:79]
	v_mfma_f32_16x16x32_bf16 v[72:75], v[160:163], v[232:235], v[72:75]
	v_mfma_f32_16x16x32_bf16 v[124:127], v[156:159], v[212:215], v[124:127]
	v_mfma_f32_16x16x32_bf16 v[120:123], v[164:167], v[212:215], v[120:123]
	v_mfma_f32_16x16x32_bf16 v[108:111], v[156:159], v[220:223], v[108:111]
	v_mfma_f32_16x16x32_bf16 v[104:107], v[164:167], v[220:223], v[104:107]
	v_mfma_f32_16x16x32_bf16 v[92:95], v[156:159], v[228:231], v[92:95]
	v_mfma_f32_16x16x32_bf16 v[88:91], v[164:167], v[228:231], v[88:91]
	v_mfma_f32_16x16x32_bf16 v[76:79], v[156:159], v[236:239], v[76:79]
	v_mfma_f32_16x16x32_bf16 v[72:75], v[164:167], v[236:239], v[72:75]
	s_setprio 0
	s_setprio 1
	v_mfma_f32_16x16x32_bf16 v[116:119], v[168:171], v[208:211], v[116:119]
	v_mfma_f32_16x16x32_bf16 v[112:115], v[176:179], v[208:211], v[112:115]
	v_mfma_f32_16x16x32_bf16 v[100:103], v[168:171], v[216:219], v[100:103]
	v_mfma_f32_16x16x32_bf16 v[96:99], v[176:179], v[216:219], v[96:99]
	v_mfma_f32_16x16x32_bf16 v[84:87], v[168:171], v[224:227], v[84:87]
	v_mfma_f32_16x16x32_bf16 v[80:83], v[176:179], v[224:227], v[80:83]
	v_mfma_f32_16x16x32_bf16 v[68:71], v[168:171], v[232:235], v[68:71]
	v_mfma_f32_16x16x32_bf16 v[64:67], v[176:179], v[232:235], v[64:67]
	v_mfma_f32_16x16x32_bf16 v[116:119], v[172:175], v[212:215], v[116:119]
	v_mfma_f32_16x16x32_bf16 v[112:115], v[204:207], v[212:215], v[112:115]
	v_mfma_f32_16x16x32_bf16 v[100:103], v[172:175], v[220:223], v[100:103]
	v_mfma_f32_16x16x32_bf16 v[96:99], v[204:207], v[220:223], v[96:99]
	v_mfma_f32_16x16x32_bf16 v[84:87], v[172:175], v[228:231], v[84:87]
	v_mfma_f32_16x16x32_bf16 v[80:83], v[204:207], v[228:231], v[80:83]
	v_mfma_f32_16x16x32_bf16 v[68:71], v[172:175], v[236:239], v[68:71]
	v_mfma_f32_16x16x32_bf16 v[64:67], v[204:207], v[236:239], v[64:67]
	s_setprio 0
	s_barrier
	s_add_i32 s4, s74, s1
	v_lshl_add_u64 v[180:181], s[34:35], 0, v[144:145]
	s_mov_b32 m0, s4
	ds_read_b128 v[208:211], v155 offset:16384
	ds_read_b128 v[212:215], v155 offset:17408
	ds_read_b128 v[216:219], v155 offset:18432
	ds_read_b128 v[220:223], v155 offset:19456
	ds_read_b128 v[224:227], v155 offset:20480
	ds_read_b128 v[228:231], v155 offset:21504
	ds_read_b128 v[232:235], v155 offset:22528
	ds_read_b128 v[236:239], v155 offset:23552
	global_load_lds_dwordx4 v[180:181], off
	s_add_i32 m0, s4, 0x2000
	s_add_u32 s4, s34, 0x40000
	v_lshl_add_u64 v[202:203], s[34:35], 0, v[128:129]
	s_addc_u32 s5, s35, 0
	s_add_i32 s74, s75, s1
	global_load_lds_dwordx4 v[202:203], off
	v_lshl_add_u64 v[240:241], s[4:5], 0, v[144:145]
	s_mov_b32 m0, s74
	v_lshl_add_u64 v[242:243], s[60:61], 0, v[130:131]
	global_load_lds_dwordx4 v[240:241], off
	v_lshl_add_u64 v[240:241], s[4:5], 0, v[128:129]
	s_add_i32 m0, s74, 0x2000
	s_nop 0
	global_load_lds_dwordx4 v[240:241], off
	v_lshl_add_u64 v[240:241], s[60:61], 0, v[132:133]
	s_mov_b32 m0, s59
	s_nop 0
	global_load_lds_dwordx4 v[240:241], off
	s_mov_b32 m0, s64
	s_nop 0
	global_load_lds_dwordx4 v[242:243], off
	s_waitcnt vmcnt(8)
	s_waitcnt lgkmcnt(0)
	s_barrier
	s_setprio 1
	s_waitcnt lgkmcnt(0)
	v_mfma_f32_16x16x32_bf16 v[60:63], v[138:141], v[208:211], v[60:63]
	v_mfma_f32_16x16x32_bf16 v[56:59], v[160:163], v[208:211], v[56:59]
	v_mfma_f32_16x16x32_bf16 v[44:47], v[138:141], v[216:219], v[44:47]
	v_mfma_f32_16x16x32_bf16 v[40:43], v[160:163], v[216:219], v[40:43]
	v_mfma_f32_16x16x32_bf16 v[28:31], v[138:141], v[224:227], v[28:31]
	v_mfma_f32_16x16x32_bf16 v[24:27], v[160:163], v[224:227], v[24:27]
	v_mfma_f32_16x16x32_bf16 v[12:15], v[138:141], v[232:235], v[12:15]
	v_mfma_f32_16x16x32_bf16 v[8:11], v[160:163], v[232:235], v[8:11]
	v_mfma_f32_16x16x32_bf16 v[60:63], v[156:159], v[212:215], v[60:63]
	v_mfma_f32_16x16x32_bf16 v[56:59], v[164:167], v[212:215], v[56:59]
	v_mfma_f32_16x16x32_bf16 v[44:47], v[156:159], v[220:223], v[44:47]
	v_mfma_f32_16x16x32_bf16 v[40:43], v[164:167], v[220:223], v[40:43]
	v_mfma_f32_16x16x32_bf16 v[28:31], v[156:159], v[228:231], v[28:31]
	v_mfma_f32_16x16x32_bf16 v[24:27], v[164:167], v[228:231], v[24:27]
	v_mfma_f32_16x16x32_bf16 v[12:15], v[156:159], v[236:239], v[12:15]
	v_mfma_f32_16x16x32_bf16 v[8:11], v[164:167], v[236:239], v[8:11]
	s_setprio 0
	s_setprio 1
	v_mfma_f32_16x16x32_bf16 v[52:55], v[168:171], v[208:211], v[52:55]
	v_mfma_f32_16x16x32_bf16 v[48:51], v[176:179], v[208:211], v[48:51]
	v_mfma_f32_16x16x32_bf16 v[36:39], v[168:171], v[216:219], v[36:39]
	v_mfma_f32_16x16x32_bf16 v[32:35], v[176:179], v[216:219], v[32:35]
	v_mfma_f32_16x16x32_bf16 v[20:23], v[168:171], v[224:227], v[20:23]
	v_mfma_f32_16x16x32_bf16 v[16:19], v[176:179], v[224:227], v[16:19]
	v_mfma_f32_16x16x32_bf16 v[4:7], v[168:171], v[232:235], v[4:7]
	v_mfma_f32_16x16x32_bf16 v[0:3], v[176:179], v[232:235], v[0:3]
	v_mfma_f32_16x16x32_bf16 v[52:55], v[172:175], v[212:215], v[52:55]
	v_mfma_f32_16x16x32_bf16 v[48:51], v[204:207], v[212:215], v[48:51]
	v_mfma_f32_16x16x32_bf16 v[36:39], v[172:175], v[220:223], v[36:39]
	v_mfma_f32_16x16x32_bf16 v[32:35], v[204:207], v[220:223], v[32:35]
	v_mfma_f32_16x16x32_bf16 v[20:23], v[172:175], v[228:231], v[20:23]
	v_mfma_f32_16x16x32_bf16 v[16:19], v[204:207], v[228:231], v[16:19]
	v_mfma_f32_16x16x32_bf16 v[4:7], v[172:175], v[236:239], v[4:7]
	v_mfma_f32_16x16x32_bf16 v[0:3], v[204:207], v[236:239], v[0:3]
	s_setprio 0
	s_barrier
	s_add_i32 s74, 0, 0x18000
	s_add_i32 s75, 0, 0x1c000
	v_add_u32_e32 v164, s74, v143
	v_add_u32_e32 v204, s75, v143
	ds_read_b128 v[138:141], v164
	ds_read_b128 v[156:159], v164 offset:1024
	ds_read_b128 v[160:163], v164 offset:2048
	ds_read_b128 v[164:167], v164 offset:3072
	ds_read_b128 v[168:171], v204
	ds_read_b128 v[172:175], v204 offset:1024
	ds_read_b128 v[176:179], v204 offset:2048
	ds_read_b128 v[204:207], v204 offset:3072
	s_add_u32 s4, s60, 0x40000
	s_addc_u32 s5, s61, 0
	s_mov_b32 m0, s65
	v_lshl_add_u64 v[244:245], s[4:5], 0, v[132:133]
	ds_read_b128 v[208:211], v155 offset:32768
	ds_read_b128 v[212:215], v155 offset:33792
	ds_read_b128 v[216:219], v155 offset:34816
	ds_read_b128 v[220:223], v155 offset:35840
	ds_read_b128 v[224:227], v155 offset:36864
	ds_read_b128 v[228:231], v155 offset:37888
	ds_read_b128 v[232:235], v155 offset:38912
	ds_read_b128 v[236:239], v155 offset:39936
	global_load_lds_dwordx4 v[244:245], off
	v_lshl_add_u64 v[244:245], s[4:5], 0, v[130:131]
	s_mov_b32 m0, s66
	s_nop 0
	global_load_lds_dwordx4 v[244:245], off
	s_waitcnt vmcnt(8)
	s_waitcnt lgkmcnt(0)
	s_barrier
	s_setprio 1
	s_waitcnt lgkmcnt(0)
	v_mfma_f32_16x16x32_bf16 v[124:127], v[138:141], v[208:211], v[124:127]
	v_mfma_f32_16x16x32_bf16 v[120:123], v[160:163], v[208:211], v[120:123]
	v_mfma_f32_16x16x32_bf16 v[108:111], v[138:141], v[216:219], v[108:111]
	v_mfma_f32_16x16x32_bf16 v[104:107], v[160:163], v[216:219], v[104:107]
	v_mfma_f32_16x16x32_bf16 v[92:95], v[138:141], v[224:227], v[92:95]
	v_mfma_f32_16x16x32_bf16 v[88:91], v[160:163], v[224:227], v[88:91]
	v_mfma_f32_16x16x32_bf16 v[76:79], v[138:141], v[232:235], v[76:79]
	v_mfma_f32_16x16x32_bf16 v[72:75], v[160:163], v[232:235], v[72:75]
	v_mfma_f32_16x16x32_bf16 v[124:127], v[156:159], v[212:215], v[124:127]
	v_mfma_f32_16x16x32_bf16 v[120:123], v[164:167], v[212:215], v[120:123]
	v_mfma_f32_16x16x32_bf16 v[108:111], v[156:159], v[220:223], v[108:111]
	v_mfma_f32_16x16x32_bf16 v[104:107], v[164:167], v[220:223], v[104:107]
	v_mfma_f32_16x16x32_bf16 v[92:95], v[156:159], v[228:231], v[92:95]
	v_mfma_f32_16x16x32_bf16 v[88:91], v[164:167], v[228:231], v[88:91]
	v_mfma_f32_16x16x32_bf16 v[76:79], v[156:159], v[236:239], v[76:79]
	v_mfma_f32_16x16x32_bf16 v[72:75], v[164:167], v[236:239], v[72:75]
	s_setprio 0
	s_setprio 1
	v_mfma_f32_16x16x32_bf16 v[116:119], v[168:171], v[208:211], v[116:119]
	v_mfma_f32_16x16x32_bf16 v[112:115], v[176:179], v[208:211], v[112:115]
	v_mfma_f32_16x16x32_bf16 v[100:103], v[168:171], v[216:219], v[100:103]
	v_mfma_f32_16x16x32_bf16 v[96:99], v[176:179], v[216:219], v[96:99]
	v_mfma_f32_16x16x32_bf16 v[84:87], v[168:171], v[224:227], v[84:87]
	v_mfma_f32_16x16x32_bf16 v[80:83], v[176:179], v[224:227], v[80:83]
	v_mfma_f32_16x16x32_bf16 v[68:71], v[168:171], v[232:235], v[68:71]
	v_mfma_f32_16x16x32_bf16 v[64:67], v[176:179], v[232:235], v[64:67]
	v_mfma_f32_16x16x32_bf16 v[116:119], v[172:175], v[212:215], v[116:119]
	v_mfma_f32_16x16x32_bf16 v[112:115], v[204:207], v[212:215], v[112:115]
	v_mfma_f32_16x16x32_bf16 v[100:103], v[172:175], v[220:223], v[100:103]
	v_mfma_f32_16x16x32_bf16 v[96:99], v[204:207], v[220:223], v[96:99]
	v_mfma_f32_16x16x32_bf16 v[84:87], v[172:175], v[228:231], v[84:87]
	v_mfma_f32_16x16x32_bf16 v[80:83], v[204:207], v[228:231], v[80:83]
	v_mfma_f32_16x16x32_bf16 v[68:71], v[172:175], v[236:239], v[68:71]
	v_mfma_f32_16x16x32_bf16 v[64:67], v[204:207], v[236:239], v[64:67]
	s_setprio 0
	s_barrier
	s_add_i32 s4, s74, s1
	v_lshl_add_u64 v[180:181], v[180:181], 0, s[26:27]
	s_mov_b32 m0, s4
	ds_read_b128 v[208:211], v155 offset:49152
	ds_read_b128 v[212:215], v155 offset:50176
	ds_read_b128 v[216:219], v155 offset:51200
	ds_read_b128 v[220:223], v155 offset:52224
	ds_read_b128 v[224:227], v155 offset:53248
	ds_read_b128 v[228:231], v155 offset:54272
	ds_read_b128 v[232:235], v155 offset:55296
	ds_read_b128 v[236:239], v155 offset:56320
	global_load_lds_dwordx4 v[180:181], off
	s_add_i32 m0, s4, 0x2000
	s_add_u32 s4, s34, 0x40080
	v_lshl_add_u64 v[180:181], v[202:203], 0, s[26:27]
	s_addc_u32 s5, s35, 0
	s_add_i32 s34, s75, s1
	global_load_lds_dwordx4 v[180:181], off
	v_lshl_add_u64 v[180:181], s[4:5], 0, v[144:145]
	s_mov_b32 m0, s34
	s_nop 0
	global_load_lds_dwordx4 v[180:181], off
	v_lshl_add_u64 v[180:181], s[4:5], 0, v[128:129]
	s_add_i32 m0, s34, 0x2000
	s_nop 0
	global_load_lds_dwordx4 v[180:181], off
	v_lshl_add_u64 v[180:181], v[240:241], 0, s[26:27]
	s_mov_b32 m0, s67
	s_nop 0
	global_load_lds_dwordx4 v[180:181], off
	v_lshl_add_u64 v[180:181], v[242:243], 0, s[26:27]
	s_mov_b32 m0, s68
	s_nop 0
	global_load_lds_dwordx4 v[180:181], off
	s_waitcnt vmcnt(8)
	s_waitcnt lgkmcnt(0)
	s_barrier
	s_setprio 1
	s_waitcnt lgkmcnt(0)
	v_mfma_f32_16x16x32_bf16 v[60:63], v[138:141], v[208:211], v[60:63]
	v_mfma_f32_16x16x32_bf16 v[56:59], v[160:163], v[208:211], v[56:59]
	v_mfma_f32_16x16x32_bf16 v[44:47], v[138:141], v[216:219], v[44:47]
	v_mfma_f32_16x16x32_bf16 v[40:43], v[160:163], v[216:219], v[40:43]
	v_mfma_f32_16x16x32_bf16 v[28:31], v[138:141], v[224:227], v[28:31]
	v_mfma_f32_16x16x32_bf16 v[24:27], v[160:163], v[224:227], v[24:27]
	v_mfma_f32_16x16x32_bf16 v[12:15], v[138:141], v[232:235], v[12:15]
	v_mfma_f32_16x16x32_bf16 v[8:11], v[160:163], v[232:235], v[8:11]
	v_mfma_f32_16x16x32_bf16 v[60:63], v[156:159], v[212:215], v[60:63]
	v_mfma_f32_16x16x32_bf16 v[56:59], v[164:167], v[212:215], v[56:59]
	v_mfma_f32_16x16x32_bf16 v[44:47], v[156:159], v[220:223], v[44:47]
	v_mfma_f32_16x16x32_bf16 v[40:43], v[164:167], v[220:223], v[40:43]
	v_mfma_f32_16x16x32_bf16 v[28:31], v[156:159], v[228:231], v[28:31]
	v_mfma_f32_16x16x32_bf16 v[24:27], v[164:167], v[228:231], v[24:27]
	v_mfma_f32_16x16x32_bf16 v[12:15], v[156:159], v[236:239], v[12:15]
	v_mfma_f32_16x16x32_bf16 v[8:11], v[164:167], v[236:239], v[8:11]
	s_setprio 0
	s_setprio 1
	v_mfma_f32_16x16x32_bf16 v[52:55], v[168:171], v[208:211], v[52:55]
	v_mfma_f32_16x16x32_bf16 v[48:51], v[176:179], v[208:211], v[48:51]
	v_mfma_f32_16x16x32_bf16 v[36:39], v[168:171], v[216:219], v[36:39]
	v_mfma_f32_16x16x32_bf16 v[32:35], v[176:179], v[216:219], v[32:35]
	v_mfma_f32_16x16x32_bf16 v[20:23], v[168:171], v[224:227], v[20:23]
	v_mfma_f32_16x16x32_bf16 v[16:19], v[176:179], v[224:227], v[16:19]
	v_mfma_f32_16x16x32_bf16 v[4:7], v[168:171], v[232:235], v[4:7]
	v_mfma_f32_16x16x32_bf16 v[0:3], v[176:179], v[232:235], v[0:3]
	v_mfma_f32_16x16x32_bf16 v[52:55], v[172:175], v[212:215], v[52:55]
	v_mfma_f32_16x16x32_bf16 v[48:51], v[204:207], v[212:215], v[48:51]
	v_mfma_f32_16x16x32_bf16 v[36:39], v[172:175], v[220:223], v[36:39]
	v_mfma_f32_16x16x32_bf16 v[32:35], v[204:207], v[220:223], v[32:35]
	v_mfma_f32_16x16x32_bf16 v[20:23], v[172:175], v[228:231], v[20:23]
	v_mfma_f32_16x16x32_bf16 v[16:19], v[204:207], v[228:231], v[16:19]
	v_mfma_f32_16x16x32_bf16 v[4:7], v[172:175], v[236:239], v[4:7]
	v_mfma_f32_16x16x32_bf16 v[0:3], v[204:207], v[236:239], v[0:3]
	s_setprio 0
	s_barrier
	s_add_i32 s73, s73, 2
	s_add_u32 s2, s2, 0x100
	s_addc_u32 s3, s3, 0
	s_add_u32 s71, s71, 0x100
	s_addc_u32 s72, s72, 0
	s_cmp_gt_u32 s73, 13
	s_cbranch_scc0 .LBB0_1305
	v_lshl_add_u32 v140, s58, 8, v142
	v_ashrrev_i32_e32 v141, 31, v140
	v_lshl_add_u64 v[156:157], v[140:141], 4, s[44:45]
	global_load_dwordx4 v[208:211], v[156:157], off
	global_load_dwordx4 v[212:215], v[156:157], off offset:256
	global_load_dwordx4 v[216:219], v[156:157], off offset:512
	global_load_dwordx4 v[220:223], v[156:157], off offset:768
	global_load_dwordx4 v[224:227], v[156:157], off offset:2048
	global_load_dwordx4 v[228:231], v[156:157], off offset:2304
	global_load_dwordx4 v[232:235], v[156:157], off offset:2560
	global_load_dwordx4 v[236:239], v[156:157], off offset:2816
	s_and_b64 vcc, exec, s[46:47]
	s_cbranch_vccz .LBB0_1308
	s_barrier
.LBB0_1308:
	v_lshl_or_b32 v164, s33, 8, v154
	v_mov_b32_e32 v176, 0xbfb8aa3b
	v_ashrrev_i32_e32 v164, 1, v164
	v_ashrrev_i32_e32 v165, 31, v164
	v_mov_b32_e32 v177, 0xbfb8aa3b
	v_lshl_add_u64 v[138:139], v[164:165], 1, s[42:43]
	s_waitcnt vmcnt(0)
	v_add_f32_e32 v208, v209, v208
	v_add_f32_e32 v212, v213, v212
	v_add_f32_e32 v216, v217, v216
	v_add_f32_e32 v220, v221, v220
	v_add_f32_e32 v224, v225, v224
	v_add_f32_e32 v228, v229, v228
	v_add_f32_e32 v232, v233, v232
	v_add_f32_e32 v236, v237, v236
	v_add_f32_e32 v210, v210, v211
	v_add_f32_e32 v214, v214, v215
	v_add_f32_e32 v218, v218, v219
	v_add_f32_e32 v222, v222, v223
	v_add_f32_e32 v226, v226, v227
	v_add_f32_e32 v230, v230, v231
	v_add_f32_e32 v234, v234, v235
	v_add_f32_e32 v238, v238, v239
	v_add_f32_e32 v208, v208, v210
	v_add_f32_e32 v212, v212, v214
	v_add_f32_e32 v216, v216, v218
	v_add_f32_e32 v220, v220, v222
	v_add_f32_e32 v224, v224, v226
	v_add_f32_e32 v228, v228, v230
	v_add_f32_e32 v232, v232, v234
	v_add_f32_e32 v236, v236, v238
	v_fmamk_f32 v208, v208, 0x3a800000, v184
	v_fmamk_f32 v212, v212, 0x3a800000, v184
	v_fmamk_f32 v216, v216, 0x3a800000, v184
	v_fmamk_f32 v220, v220, 0x3a800000, v184
	v_fmamk_f32 v224, v224, 0x3a800000, v184
	v_fmamk_f32 v228, v228, 0x3a800000, v184
	v_fmamk_f32 v232, v232, 0x3a800000, v184
	v_fmamk_f32 v236, v236, 0x3a800000, v184
	v_rsq_f32_e32 v160, v208
	v_rsq_f32_e32 v162, v212
	v_rsq_f32_e32 v164, v216
	v_rsq_f32_e32 v166, v220
	v_rsq_f32_e32 v168, v224
	v_rsq_f32_e32 v170, v228
	v_rsq_f32_e32 v172, v232
	v_rsq_f32_e32 v174, v236
	v_pk_mul_f32 v[124:125], v[124:125], v[160:161] op_sel_hi:[1,0]
	v_pk_mul_f32 v[126:127], v[126:127], v[160:161] op_sel_hi:[1,0]
	v_pk_mul_f32 v[116:117], v[116:117], v[160:161] op_sel_hi:[1,0]
	v_pk_mul_f32 v[118:119], v[118:119], v[160:161] op_sel_hi:[1,0]
	v_pk_mul_f32 v[120:121], v[120:121], v[160:161] op_sel_hi:[1,0]
	v_pk_mul_f32 v[122:123], v[122:123], v[160:161] op_sel_hi:[1,0]
	v_pk_mul_f32 v[112:113], v[112:113], v[160:161] op_sel_hi:[1,0]
	v_pk_mul_f32 v[114:115], v[114:115], v[160:161] op_sel_hi:[1,0]
	v_pk_mul_f32 v[232:233], v[124:125], v[176:177] op_sel_hi:[1,0]
	v_pk_mul_f32 v[234:235], v[126:127], v[176:177] op_sel_hi:[1,0]
	v_pk_mul_f32 v[236:237], v[116:117], v[176:177] op_sel_hi:[1,0]
	v_pk_mul_f32 v[238:239], v[118:119], v[176:177] op_sel_hi:[1,0]
	v_mad_i64_i32 v[216:217], s[2:3], v140, s78, v[138:139]
	v_exp_f32_e32 v232, v232
	v_exp_f32_e32 v233, v233
	v_exp_f32_e32 v234, v234
	v_exp_f32_e32 v235, v235
	v_exp_f32_e32 v236, v236
	v_exp_f32_e32 v237, v237
	v_exp_f32_e32 v238, v238
	v_exp_f32_e32 v239, v239
	v_pk_add_f32 v[232:233], v[232:233], 1.0 op_sel_hi:[1,0]
	v_pk_add_f32 v[234:235], v[234:235], 1.0 op_sel_hi:[1,0]
	v_pk_add_f32 v[236:237], v[236:237], 1.0 op_sel_hi:[1,0]
	v_pk_add_f32 v[238:239], v[238:239], 1.0 op_sel_hi:[1,0]
	v_rcp_f32_e32 v232, v232
	v_rcp_f32_e32 v233, v233
	v_rcp_f32_e32 v234, v234
	v_rcp_f32_e32 v235, v235
	v_rcp_f32_e32 v236, v236
	v_rcp_f32_e32 v237, v237
	v_rcp_f32_e32 v238, v238
	v_rcp_f32_e32 v239, v239
	v_pk_mul_f32 v[232:233], v[124:125], v[232:233]
	v_pk_mul_f32 v[234:235], v[126:127], v[234:235]
	v_pk_mul_f32 v[236:237], v[116:117], v[236:237]
	v_pk_mul_f32 v[238:239], v[118:119], v[238:239]
	v_pk_mul_f32 v[232:233], v[120:121], v[232:233]
	v_pk_mul_f32 v[234:235], v[122:123], v[234:235]
	v_pk_mul_f32 v[236:237], v[112:113], v[236:237]
	v_pk_mul_f32 v[238:239], v[114:115], v[238:239]
	v_cvt_pk_bf16_f32 v224, v232, v233
	v_cvt_pk_bf16_f32 v225, v234, v235
	v_cvt_pk_bf16_f32 v226, v236, v237
	v_cvt_pk_bf16_f32 v227, v238, v239
	global_store_dwordx2 v[216:217], v[224:225], off
	global_store_dwordx2 v[216:217], v[226:227], off offset:128
	v_pk_mul_f32 v[108:109], v[108:109], v[162:163] op_sel_hi:[1,0]
	v_pk_mul_f32 v[110:111], v[110:111], v[162:163] op_sel_hi:[1,0]
	v_pk_mul_f32 v[100:101], v[100:101], v[162:163] op_sel_hi:[1,0]
	v_pk_mul_f32 v[102:103], v[102:103], v[162:163] op_sel_hi:[1,0]
	v_pk_mul_f32 v[104:105], v[104:105], v[162:163] op_sel_hi:[1,0]
	v_pk_mul_f32 v[106:107], v[106:107], v[162:163] op_sel_hi:[1,0]
	v_pk_mul_f32 v[96:97], v[96:97], v[162:163] op_sel_hi:[1,0]
	v_pk_mul_f32 v[98:99], v[98:99], v[162:163] op_sel_hi:[1,0]
	v_add_u32_e32 v141, 0x10, v140
	v_pk_mul_f32 v[232:233], v[108:109], v[176:177] op_sel_hi:[1,0]
	v_pk_mul_f32 v[234:235], v[110:111], v[176:177] op_sel_hi:[1,0]
	v_pk_mul_f32 v[236:237], v[100:101], v[176:177] op_sel_hi:[1,0]
	v_pk_mul_f32 v[238:239], v[102:103], v[176:177] op_sel_hi:[1,0]
	v_mad_i64_i32 v[218:219], s[2:3], v141, s78, v[138:139]
	v_exp_f32_e32 v232, v232
	v_exp_f32_e32 v233, v233
	v_exp_f32_e32 v234, v234
	v_exp_f32_e32 v235, v235
	v_exp_f32_e32 v236, v236
	v_exp_f32_e32 v237, v237
	v_exp_f32_e32 v238, v238
	v_exp_f32_e32 v239, v239
	v_pk_add_f32 v[232:233], v[232:233], 1.0 op_sel_hi:[1,0]
	v_pk_add_f32 v[234:235], v[234:235], 1.0 op_sel_hi:[1,0]
	v_pk_add_f32 v[236:237], v[236:237], 1.0 op_sel_hi:[1,0]
	v_pk_add_f32 v[238:239], v[238:239], 1.0 op_sel_hi:[1,0]
	v_rcp_f32_e32 v232, v232
	v_rcp_f32_e32 v233, v233
	v_rcp_f32_e32 v234, v234
	v_rcp_f32_e32 v235, v235
	v_rcp_f32_e32 v236, v236
	v_rcp_f32_e32 v237, v237
	v_rcp_f32_e32 v238, v238
	v_rcp_f32_e32 v239, v239
	v_pk_mul_f32 v[232:233], v[108:109], v[232:233]
	v_pk_mul_f32 v[234:235], v[110:111], v[234:235]
	v_pk_mul_f32 v[236:237], v[100:101], v[236:237]
	v_pk_mul_f32 v[238:239], v[102:103], v[238:239]
	v_pk_mul_f32 v[232:233], v[104:105], v[232:233]
	v_pk_mul_f32 v[234:235], v[106:107], v[234:235]
	v_pk_mul_f32 v[236:237], v[96:97], v[236:237]
	v_pk_mul_f32 v[238:239], v[98:99], v[238:239]
	v_cvt_pk_bf16_f32 v228, v232, v233
	v_cvt_pk_bf16_f32 v229, v234, v235
	v_cvt_pk_bf16_f32 v230, v236, v237
	v_cvt_pk_bf16_f32 v231, v238, v239
	global_store_dwordx2 v[218:219], v[228:229], off
	global_store_dwordx2 v[218:219], v[230:231], off offset:128
	v_pk_mul_f32 v[92:93], v[92:93], v[164:165] op_sel_hi:[1,0]
	v_pk_mul_f32 v[94:95], v[94:95], v[164:165] op_sel_hi:[1,0]
	v_pk_mul_f32 v[84:85], v[84:85], v[164:165] op_sel_hi:[1,0]
	v_pk_mul_f32 v[86:87], v[86:87], v[164:165] op_sel_hi:[1,0]
	v_pk_mul_f32 v[88:89], v[88:89], v[164:165] op_sel_hi:[1,0]
	v_pk_mul_f32 v[90:91], v[90:91], v[164:165] op_sel_hi:[1,0]
	v_pk_mul_f32 v[80:81], v[80:81], v[164:165] op_sel_hi:[1,0]
	v_pk_mul_f32 v[82:83], v[82:83], v[164:165] op_sel_hi:[1,0]
	v_add_u32_e32 v141, 0x20, v140
	v_pk_mul_f32 v[232:233], v[92:93], v[176:177] op_sel_hi:[1,0]
	v_pk_mul_f32 v[234:235], v[94:95], v[176:177] op_sel_hi:[1,0]
	v_pk_mul_f32 v[236:237], v[84:85], v[176:177] op_sel_hi:[1,0]
	v_pk_mul_f32 v[238:239], v[86:87], v[176:177] op_sel_hi:[1,0]
	v_mad_i64_i32 v[220:221], s[2:3], v141, s78, v[138:139]
	v_exp_f32_e32 v232, v232
	v_exp_f32_e32 v233, v233
	v_exp_f32_e32 v234, v234
	v_exp_f32_e32 v235, v235
	v_exp_f32_e32 v236, v236
	v_exp_f32_e32 v237, v237
	v_exp_f32_e32 v238, v238
	v_exp_f32_e32 v239, v239
	v_pk_add_f32 v[232:233], v[232:233], 1.0 op_sel_hi:[1,0]
	v_pk_add_f32 v[234:235], v[234:235], 1.0 op_sel_hi:[1,0]
	v_pk_add_f32 v[236:237], v[236:237], 1.0 op_sel_hi:[1,0]
	v_pk_add_f32 v[238:239], v[238:239], 1.0 op_sel_hi:[1,0]
	v_rcp_f32_e32 v232, v232
	v_rcp_f32_e32 v233, v233
	v_rcp_f32_e32 v234, v234
	v_rcp_f32_e32 v235, v235
	v_rcp_f32_e32 v236, v236
	v_rcp_f32_e32 v237, v237
	v_rcp_f32_e32 v238, v238
	v_rcp_f32_e32 v239, v239
	v_pk_mul_f32 v[232:233], v[92:93], v[232:233]
	v_pk_mul_f32 v[234:235], v[94:95], v[234:235]
	v_pk_mul_f32 v[236:237], v[84:85], v[236:237]
	v_pk_mul_f32 v[238:239], v[86:87], v[238:239]
	v_pk_mul_f32 v[232:233], v[88:89], v[232:233]
	v_pk_mul_f32 v[234:235], v[90:91], v[234:235]
	v_pk_mul_f32 v[236:237], v[80:81], v[236:237]
	v_pk_mul_f32 v[238:239], v[82:83], v[238:239]
	v_cvt_pk_bf16_f32 v224, v232, v233
	v_cvt_pk_bf16_f32 v225, v234, v235
	v_cvt_pk_bf16_f32 v226, v236, v237
	v_cvt_pk_bf16_f32 v227, v238, v239
	global_store_dwordx2 v[220:221], v[224:225], off
	global_store_dwordx2 v[220:221], v[226:227], off offset:128
	v_pk_mul_f32 v[76:77], v[76:77], v[166:167] op_sel_hi:[1,0]
	v_pk_mul_f32 v[78:79], v[78:79], v[166:167] op_sel_hi:[1,0]
	v_pk_mul_f32 v[68:69], v[68:69], v[166:167] op_sel_hi:[1,0]
	v_pk_mul_f32 v[70:71], v[70:71], v[166:167] op_sel_hi:[1,0]
	v_pk_mul_f32 v[72:73], v[72:73], v[166:167] op_sel_hi:[1,0]
	v_pk_mul_f32 v[74:75], v[74:75], v[166:167] op_sel_hi:[1,0]
	v_pk_mul_f32 v[64:65], v[64:65], v[166:167] op_sel_hi:[1,0]
	v_pk_mul_f32 v[66:67], v[66:67], v[166:167] op_sel_hi:[1,0]
	v_add_u32_e32 v141, 0x30, v140
	v_pk_mul_f32 v[232:233], v[76:77], v[176:177] op_sel_hi:[1,0]
	v_pk_mul_f32 v[234:235], v[78:79], v[176:177] op_sel_hi:[1,0]
	v_pk_mul_f32 v[236:237], v[68:69], v[176:177] op_sel_hi:[1,0]
	v_pk_mul_f32 v[238:239], v[70:71], v[176:177] op_sel_hi:[1,0]
	v_mad_i64_i32 v[222:223], s[2:3], v141, s78, v[138:139]
	v_exp_f32_e32 v232, v232
	v_exp_f32_e32 v233, v233
	v_exp_f32_e32 v234, v234
	v_exp_f32_e32 v235, v235
	v_exp_f32_e32 v236, v236
	v_exp_f32_e32 v237, v237
	v_exp_f32_e32 v238, v238
	v_exp_f32_e32 v239, v239
	v_pk_add_f32 v[232:233], v[232:233], 1.0 op_sel_hi:[1,0]
	v_pk_add_f32 v[234:235], v[234:235], 1.0 op_sel_hi:[1,0]
	v_pk_add_f32 v[236:237], v[236:237], 1.0 op_sel_hi:[1,0]
	v_pk_add_f32 v[238:239], v[238:239], 1.0 op_sel_hi:[1,0]
	v_rcp_f32_e32 v232, v232
	v_rcp_f32_e32 v233, v233
	v_rcp_f32_e32 v234, v234
	v_rcp_f32_e32 v235, v235
	v_rcp_f32_e32 v236, v236
	v_rcp_f32_e32 v237, v237
	v_rcp_f32_e32 v238, v238
	v_rcp_f32_e32 v239, v239
	v_pk_mul_f32 v[232:233], v[76:77], v[232:233]
	v_pk_mul_f32 v[234:235], v[78:79], v[234:235]
	v_pk_mul_f32 v[236:237], v[68:69], v[236:237]
	v_pk_mul_f32 v[238:239], v[70:71], v[238:239]
	v_pk_mul_f32 v[232:233], v[72:73], v[232:233]
	v_pk_mul_f32 v[234:235], v[74:75], v[234:235]
	v_pk_mul_f32 v[236:237], v[64:65], v[236:237]
	v_pk_mul_f32 v[238:239], v[66:67], v[238:239]
	v_cvt_pk_bf16_f32 v228, v232, v233
	v_cvt_pk_bf16_f32 v229, v234, v235
	v_cvt_pk_bf16_f32 v230, v236, v237
	v_cvt_pk_bf16_f32 v231, v238, v239
	global_store_dwordx2 v[222:223], v[228:229], off
	global_store_dwordx2 v[222:223], v[230:231], off offset:128
	v_pk_mul_f32 v[60:61], v[60:61], v[168:169] op_sel_hi:[1,0]
	v_pk_mul_f32 v[62:63], v[62:63], v[168:169] op_sel_hi:[1,0]
	v_pk_mul_f32 v[52:53], v[52:53], v[168:169] op_sel_hi:[1,0]
	v_pk_mul_f32 v[54:55], v[54:55], v[168:169] op_sel_hi:[1,0]
	v_pk_mul_f32 v[56:57], v[56:57], v[168:169] op_sel_hi:[1,0]
	v_pk_mul_f32 v[58:59], v[58:59], v[168:169] op_sel_hi:[1,0]
	v_pk_mul_f32 v[48:49], v[48:49], v[168:169] op_sel_hi:[1,0]
	v_pk_mul_f32 v[50:51], v[50:51], v[168:169] op_sel_hi:[1,0]
	v_add_u32_e32 v141, 0x80, v140
	v_pk_mul_f32 v[232:233], v[60:61], v[176:177] op_sel_hi:[1,0]
	v_pk_mul_f32 v[234:235], v[62:63], v[176:177] op_sel_hi:[1,0]
	v_pk_mul_f32 v[236:237], v[52:53], v[176:177] op_sel_hi:[1,0]
	v_pk_mul_f32 v[238:239], v[54:55], v[176:177] op_sel_hi:[1,0]
	v_mad_i64_i32 v[216:217], s[2:3], v141, s78, v[138:139]
	v_exp_f32_e32 v232, v232
	v_exp_f32_e32 v233, v233
	v_exp_f32_e32 v234, v234
	v_exp_f32_e32 v235, v235
	v_exp_f32_e32 v236, v236
	v_exp_f32_e32 v237, v237
	v_exp_f32_e32 v238, v238
	v_exp_f32_e32 v239, v239
	v_pk_add_f32 v[232:233], v[232:233], 1.0 op_sel_hi:[1,0]
	v_pk_add_f32 v[234:235], v[234:235], 1.0 op_sel_hi:[1,0]
	v_pk_add_f32 v[236:237], v[236:237], 1.0 op_sel_hi:[1,0]
	v_pk_add_f32 v[238:239], v[238:239], 1.0 op_sel_hi:[1,0]
	v_rcp_f32_e32 v232, v232
	v_rcp_f32_e32 v233, v233
	v_rcp_f32_e32 v234, v234
	v_rcp_f32_e32 v235, v235
	v_rcp_f32_e32 v236, v236
	v_rcp_f32_e32 v237, v237
	v_rcp_f32_e32 v238, v238
	v_rcp_f32_e32 v239, v239
	v_pk_mul_f32 v[232:233], v[60:61], v[232:233]
	v_pk_mul_f32 v[234:235], v[62:63], v[234:235]
	v_pk_mul_f32 v[236:237], v[52:53], v[236:237]
	v_pk_mul_f32 v[238:239], v[54:55], v[238:239]
	v_pk_mul_f32 v[232:233], v[56:57], v[232:233]
	v_pk_mul_f32 v[234:235], v[58:59], v[234:235]
	v_pk_mul_f32 v[236:237], v[48:49], v[236:237]
	v_pk_mul_f32 v[238:239], v[50:51], v[238:239]
	v_cvt_pk_bf16_f32 v224, v232, v233
	v_cvt_pk_bf16_f32 v225, v234, v235
	v_cvt_pk_bf16_f32 v226, v236, v237
	v_cvt_pk_bf16_f32 v227, v238, v239
	global_store_dwordx2 v[216:217], v[224:225], off
	global_store_dwordx2 v[216:217], v[226:227], off offset:128
	v_pk_mul_f32 v[44:45], v[44:45], v[170:171] op_sel_hi:[1,0]
	v_pk_mul_f32 v[46:47], v[46:47], v[170:171] op_sel_hi:[1,0]
	v_pk_mul_f32 v[36:37], v[36:37], v[170:171] op_sel_hi:[1,0]
	v_pk_mul_f32 v[38:39], v[38:39], v[170:171] op_sel_hi:[1,0]
	v_pk_mul_f32 v[40:41], v[40:41], v[170:171] op_sel_hi:[1,0]
	v_pk_mul_f32 v[42:43], v[42:43], v[170:171] op_sel_hi:[1,0]
	v_pk_mul_f32 v[32:33], v[32:33], v[170:171] op_sel_hi:[1,0]
	v_pk_mul_f32 v[34:35], v[34:35], v[170:171] op_sel_hi:[1,0]
	v_add_u32_e32 v141, 0x90, v140
	v_pk_mul_f32 v[232:233], v[44:45], v[176:177] op_sel_hi:[1,0]
	v_pk_mul_f32 v[234:235], v[46:47], v[176:177] op_sel_hi:[1,0]
	v_pk_mul_f32 v[236:237], v[36:37], v[176:177] op_sel_hi:[1,0]
	v_pk_mul_f32 v[238:239], v[38:39], v[176:177] op_sel_hi:[1,0]
	v_mad_i64_i32 v[218:219], s[2:3], v141, s78, v[138:139]
	v_exp_f32_e32 v232, v232
	v_exp_f32_e32 v233, v233
	v_exp_f32_e32 v234, v234
	v_exp_f32_e32 v235, v235
	v_exp_f32_e32 v236, v236
	v_exp_f32_e32 v237, v237
	v_exp_f32_e32 v238, v238
	v_exp_f32_e32 v239, v239
	v_pk_add_f32 v[232:233], v[232:233], 1.0 op_sel_hi:[1,0]
	v_pk_add_f32 v[234:235], v[234:235], 1.0 op_sel_hi:[1,0]
	v_pk_add_f32 v[236:237], v[236:237], 1.0 op_sel_hi:[1,0]
	v_pk_add_f32 v[238:239], v[238:239], 1.0 op_sel_hi:[1,0]
	v_rcp_f32_e32 v232, v232
	v_rcp_f32_e32 v233, v233
	v_rcp_f32_e32 v234, v234
	v_rcp_f32_e32 v235, v235
	v_rcp_f32_e32 v236, v236
	v_rcp_f32_e32 v237, v237
	v_rcp_f32_e32 v238, v238
	v_rcp_f32_e32 v239, v239
	v_pk_mul_f32 v[232:233], v[44:45], v[232:233]
	v_pk_mul_f32 v[234:235], v[46:47], v[234:235]
	v_pk_mul_f32 v[236:237], v[36:37], v[236:237]
	v_pk_mul_f32 v[238:239], v[38:39], v[238:239]
	v_pk_mul_f32 v[232:233], v[40:41], v[232:233]
	v_pk_mul_f32 v[234:235], v[42:43], v[234:235]
	v_pk_mul_f32 v[236:237], v[32:33], v[236:237]
	v_pk_mul_f32 v[238:239], v[34:35], v[238:239]
	v_cvt_pk_bf16_f32 v228, v232, v233
	v_cvt_pk_bf16_f32 v229, v234, v235
	v_cvt_pk_bf16_f32 v230, v236, v237
	v_cvt_pk_bf16_f32 v231, v238, v239
	global_store_dwordx2 v[218:219], v[228:229], off
	global_store_dwordx2 v[218:219], v[230:231], off offset:128
	v_pk_mul_f32 v[28:29], v[28:29], v[172:173] op_sel_hi:[1,0]
	v_pk_mul_f32 v[30:31], v[30:31], v[172:173] op_sel_hi:[1,0]
	v_pk_mul_f32 v[20:21], v[20:21], v[172:173] op_sel_hi:[1,0]
	v_pk_mul_f32 v[22:23], v[22:23], v[172:173] op_sel_hi:[1,0]
	v_pk_mul_f32 v[24:25], v[24:25], v[172:173] op_sel_hi:[1,0]
	v_pk_mul_f32 v[26:27], v[26:27], v[172:173] op_sel_hi:[1,0]
	v_pk_mul_f32 v[16:17], v[16:17], v[172:173] op_sel_hi:[1,0]
	v_pk_mul_f32 v[18:19], v[18:19], v[172:173] op_sel_hi:[1,0]
	v_add_u32_e32 v141, 0xa0, v140
	v_pk_mul_f32 v[232:233], v[28:29], v[176:177] op_sel_hi:[1,0]
	v_pk_mul_f32 v[234:235], v[30:31], v[176:177] op_sel_hi:[1,0]
	v_pk_mul_f32 v[236:237], v[20:21], v[176:177] op_sel_hi:[1,0]
	v_pk_mul_f32 v[238:239], v[22:23], v[176:177] op_sel_hi:[1,0]
	v_mad_i64_i32 v[220:221], s[2:3], v141, s78, v[138:139]
	v_exp_f32_e32 v232, v232
	v_exp_f32_e32 v233, v233
	v_exp_f32_e32 v234, v234
	v_exp_f32_e32 v235, v235
	v_exp_f32_e32 v236, v236
	v_exp_f32_e32 v237, v237
	v_exp_f32_e32 v238, v238
	v_exp_f32_e32 v239, v239
	v_pk_add_f32 v[232:233], v[232:233], 1.0 op_sel_hi:[1,0]
	v_pk_add_f32 v[234:235], v[234:235], 1.0 op_sel_hi:[1,0]
	v_pk_add_f32 v[236:237], v[236:237], 1.0 op_sel_hi:[1,0]
	v_pk_add_f32 v[238:239], v[238:239], 1.0 op_sel_hi:[1,0]
	v_rcp_f32_e32 v232, v232
	v_rcp_f32_e32 v233, v233
	v_rcp_f32_e32 v234, v234
	v_rcp_f32_e32 v235, v235
	v_rcp_f32_e32 v236, v236
	v_rcp_f32_e32 v237, v237
	v_rcp_f32_e32 v238, v238
	v_rcp_f32_e32 v239, v239
	v_pk_mul_f32 v[232:233], v[28:29], v[232:233]
	v_pk_mul_f32 v[234:235], v[30:31], v[234:235]
	v_pk_mul_f32 v[236:237], v[20:21], v[236:237]
	v_pk_mul_f32 v[238:239], v[22:23], v[238:239]
	v_pk_mul_f32 v[232:233], v[24:25], v[232:233]
	v_pk_mul_f32 v[234:235], v[26:27], v[234:235]
	v_pk_mul_f32 v[236:237], v[16:17], v[236:237]
	v_pk_mul_f32 v[238:239], v[18:19], v[238:239]
	v_cvt_pk_bf16_f32 v224, v232, v233
	v_cvt_pk_bf16_f32 v225, v234, v235
	v_cvt_pk_bf16_f32 v226, v236, v237
	v_cvt_pk_bf16_f32 v227, v238, v239
	global_store_dwordx2 v[220:221], v[224:225], off
	global_store_dwordx2 v[220:221], v[226:227], off offset:128
	v_pk_mul_f32 v[12:13], v[12:13], v[174:175] op_sel_hi:[1,0]
	v_pk_mul_f32 v[14:15], v[14:15], v[174:175] op_sel_hi:[1,0]
	v_pk_mul_f32 v[4:5], v[4:5], v[174:175] op_sel_hi:[1,0]
	v_pk_mul_f32 v[6:7], v[6:7], v[174:175] op_sel_hi:[1,0]
	v_pk_mul_f32 v[8:9], v[8:9], v[174:175] op_sel_hi:[1,0]
	v_pk_mul_f32 v[10:11], v[10:11], v[174:175] op_sel_hi:[1,0]
	v_pk_mul_f32 v[0:1], v[0:1], v[174:175] op_sel_hi:[1,0]
	v_pk_mul_f32 v[2:3], v[2:3], v[174:175] op_sel_hi:[1,0]
	v_add_u32_e32 v141, 0xb0, v140
	v_pk_mul_f32 v[232:233], v[12:13], v[176:177] op_sel_hi:[1,0]
	v_pk_mul_f32 v[234:235], v[14:15], v[176:177] op_sel_hi:[1,0]
	v_pk_mul_f32 v[236:237], v[4:5], v[176:177] op_sel_hi:[1,0]
	v_pk_mul_f32 v[238:239], v[6:7], v[176:177] op_sel_hi:[1,0]
	v_mad_i64_i32 v[222:223], s[2:3], v141, s78, v[138:139]
	v_exp_f32_e32 v232, v232
	v_exp_f32_e32 v233, v233
	v_exp_f32_e32 v234, v234
	v_exp_f32_e32 v235, v235
	v_exp_f32_e32 v236, v236
	v_exp_f32_e32 v237, v237
	v_exp_f32_e32 v238, v238
	v_exp_f32_e32 v239, v239
	v_pk_add_f32 v[232:233], v[232:233], 1.0 op_sel_hi:[1,0]
	v_pk_add_f32 v[234:235], v[234:235], 1.0 op_sel_hi:[1,0]
	v_pk_add_f32 v[236:237], v[236:237], 1.0 op_sel_hi:[1,0]
	v_pk_add_f32 v[238:239], v[238:239], 1.0 op_sel_hi:[1,0]
	v_rcp_f32_e32 v232, v232
	v_rcp_f32_e32 v233, v233
	v_rcp_f32_e32 v234, v234
	v_rcp_f32_e32 v235, v235
	v_rcp_f32_e32 v236, v236
	v_rcp_f32_e32 v237, v237
	v_rcp_f32_e32 v238, v238
	v_rcp_f32_e32 v239, v239
	v_pk_mul_f32 v[232:233], v[12:13], v[232:233]
	v_pk_mul_f32 v[234:235], v[14:15], v[234:235]
	v_pk_mul_f32 v[236:237], v[4:5], v[236:237]
	v_pk_mul_f32 v[238:239], v[6:7], v[238:239]
	v_pk_mul_f32 v[232:233], v[8:9], v[232:233]
	v_pk_mul_f32 v[234:235], v[10:11], v[234:235]
	v_pk_mul_f32 v[236:237], v[0:1], v[236:237]
	v_pk_mul_f32 v[238:239], v[2:3], v[238:239]
	v_cvt_pk_bf16_f32 v228, v232, v233
	v_cvt_pk_bf16_f32 v229, v234, v235
	v_cvt_pk_bf16_f32 v230, v236, v237
	v_cvt_pk_bf16_f32 v231, v238, v239
	global_store_dwordx2 v[222:223], v[228:229], off
	global_store_dwordx2 v[222:223], v[230:231], off offset:128
	s_mov_b64 s[2:3], -1
	s_andn2_b64 vcc, exec, s[38:39]
	s_cbranch_vccnz .LBB0_1301
	s_andn2_b64 vcc, exec, s[40:41]
	s_cbranch_vccnz .LBB0_1300
	s_barrier
	s_branch .LBB0_1300
